# split-K sample-row tiles redistributed: one per CU spread over all 8 XCDs (when gridDim==512) instead of all on XCD0-2 as second tiles
# speedup vs baseline: 1.0530x; 1.0178x over previous
;     ...
;   __syncthreads();
;   G2_STAGE(0); G2_STAGE(1);
;   const int fsw = (0x78 >> (((r16 >> 2) & 3) * 2)) & 3;
;   const int aoff = (wm * 128 + r16) * 64 + ((quad ^ fsw) << 4);
;   const int boff = 16384 + (wn * 64 + r16) * 64 + ((quad ^ fsw) << 4);
;   for (int kt = 0; kt < nk; kt++) {
;     if (kt + 1 < nk) asm volatile("s_waitcnt vmcnt(6)" ::: "memory");
;     else asm volatile("s_waitcnt vmcnt(0)" ::: "memory");
;     __builtin_amdgcn_s_barrier();
;     asm volatile("" ::: "memory");
;     if (kt + 2 < nk) G2_STAGE(kt + 2);
;     const char* cS = smem + (kt % 3) * 24576;
;     bf16x8 xa[8], wb[4];
; #pragma unroll
;     for (int f = 0; f < 8; f++) xa[f] = *(const bf16x8*)(cS + aoff + f * 1024);
; #pragma unroll
;     for (int f = 0; f < 4; f++) wb[f] = *(const bf16x8*)(cS + boff + f * 1024);
; #pragma unroll
;     for (int nf = 0; nf < 4; nf++)
; #pragma unroll
;       for (int mf = 0; mf < 8; mf++)
;         acc[nf][mf] = __builtin_amdgcn_mfma_f32_16x16x32_bf16(wb[nf], xa[mf], acc[nf][mf], 0, 0, 0);
;   }
.Lt11_loop:
	s_waitcnt vmcnt(6) lgkmcnt(0)
	s_barrier
	v_add_u32_e32 v144, s40, v136
	v_mfma_f32_16x16x32_bf16 v[126:129], v[184:187], v[146:149], v[126:129]
	ds_read_b128 v[200:203], v144 offset:0
	v_mfma_f32_16x16x32_bf16 v[122:125], v[184:187], v[152:155], v[122:125]
	ds_read_b128 v[204:207], v144 offset:1024
	v_mfma_f32_16x16x32_bf16 v[118:121], v[184:187], v[156:159], v[118:121]
	ds_read_b128 v[208:211], v144 offset:2048
	v_mfma_f32_16x16x32_bf16 v[114:117], v[184:187], v[162:165], v[114:117]
	ds_read_b128 v[212:215], v144 offset:3072
	v_mfma_f32_16x16x32_bf16 v[110:113], v[184:187], v[166:169], v[110:113]
	ds_read_b128 v[216:219], v144 offset:4096
	v_mfma_f32_16x16x32_bf16 v[106:109], v[184:187], v[170:173], v[106:109]
	ds_read_b128 v[220:223], v144 offset:5120
	v_mfma_f32_16x16x32_bf16 v[102:105], v[184:187], v[176:179], v[102:105]
	ds_read_b128 v[224:227], v144 offset:6144
	v_mfma_f32_16x16x32_bf16 v[98:101], v[184:187], v[180:183], v[98:101]
	ds_read_b128 v[228:231], v144 offset:7168
	v_mfma_f32_16x16x32_bf16 v[94:97], v[188:191], v[146:149], v[94:97]
	v_add_u32_e32 v144, s40, v137
	v_mfma_f32_16x16x32_bf16 v[90:93], v[188:191], v[152:155], v[90:93]
	v_mfma_f32_16x16x32_bf16 v[86:89], v[188:191], v[156:159], v[86:89]
	ds_read_b128 v[232:235], v144 offset:16384
	v_mfma_f32_16x16x32_bf16 v[82:85], v[188:191], v[162:165], v[82:85]
	ds_read_b128 v[236:239], v144 offset:17408
	v_mfma_f32_16x16x32_bf16 v[78:81], v[188:191], v[166:169], v[78:81]
	ds_read_b128 v[240:243], v144 offset:18432
	v_mfma_f32_16x16x32_bf16 v[74:77], v[188:191], v[170:173], v[74:77]
	ds_read_b128 v[244:247], v144 offset:19456
	s_add_i32 s42, s46, s41
	v_mfma_f32_16x16x32_bf16 v[70:73], v[188:191], v[176:179], v[70:73]
	s_mov_b32 m0, s42
	v_lshl_add_u64 v[142:143], v[132:133], 0, s[2:3]
	v_mfma_f32_16x16x32_bf16 v[66:69], v[188:191], v[180:183], v[66:69]
	global_load_lds_dwordx4 v[132:133], off
	s_addk_i32 m0, 0x1000
	v_mfma_f32_16x16x32_bf16 v[62:65], v[192:195], v[146:149], v[62:65]
	v_mfma_f32_16x16x32_bf16 v[58:61], v[192:195], v[152:155], v[58:61]
	v_mfma_f32_16x16x32_bf16 v[54:57], v[192:195], v[156:159], v[54:57]
	global_load_lds_dwordx4 v[142:143], off
	v_lshl_add_u64 v[142:143], v[142:143], 0, s[2:3]
	s_addk_i32 m0, 0x1000
	v_mfma_f32_16x16x32_bf16 v[50:53], v[192:195], v[162:165], v[50:53]
	v_mfma_f32_16x16x32_bf16 v[46:49], v[192:195], v[166:169], v[46:49]
	v_mfma_f32_16x16x32_bf16 v[42:45], v[192:195], v[170:173], v[42:45]
	global_load_lds_dwordx4 v[142:143], off
	v_lshl_add_u64 v[142:143], v[142:143], 0, s[2:3]
	s_addk_i32 m0, 0x1000
	v_mfma_f32_16x16x32_bf16 v[38:41], v[192:195], v[176:179], v[38:41]
	v_mfma_f32_16x16x32_bf16 v[34:37], v[192:195], v[180:183], v[34:37]
	v_mfma_f32_16x16x32_bf16 v[30:33], v[196:199], v[146:149], v[30:33]
	global_load_lds_dwordx4 v[142:143], off
	s_addk_i32 m0, 0x1000
	v_lshl_add_u64 v[142:143], v[134:135], 0, s[2:3]
	v_mfma_f32_16x16x32_bf16 v[26:29], v[196:199], v[152:155], v[26:29]
	v_mfma_f32_16x16x32_bf16 v[22:25], v[196:199], v[156:159], v[22:25]
	v_mfma_f32_16x16x32_bf16 v[18:21], v[196:199], v[162:165], v[18:21]
	global_load_lds_dwordx4 v[134:135], off
	s_addk_i32 m0, 0x1000
	v_lshl_add_u64 v[132:133], v[132:133], 0, s[12:13]
	v_mfma_f32_16x16x32_bf16 v[14:17], v[196:199], v[166:169], v[14:17]
	v_mfma_f32_16x16x32_bf16 v[10:13], v[196:199], v[170:173], v[10:13]
	v_mfma_f32_16x16x32_bf16 v[6:9], v[196:199], v[176:179], v[6:9]
	global_load_lds_dwordx4 v[142:143], off
	v_lshl_add_u64 v[134:135], v[134:135], 0, s[4:5]
	v_mfma_f32_16x16x32_bf16 v[2:5], v[196:199], v[180:183], v[2:5]
	s_mov_b32 s41, s40
	s_add_i32 s40, s40, 0x6000
	s_cmp_eq_u32 s40, 0x12000
	s_cselect_b32 s40, 0, s40
	s_waitcnt vmcnt(6) lgkmcnt(0)
	s_barrier
	v_add_u32_e32 v144, s40, v136
	v_mfma_f32_16x16x32_bf16 v[126:129], v[232:235], v[200:203], v[126:129]
	ds_read_b128 v[146:149], v144 offset:0
	v_mfma_f32_16x16x32_bf16 v[122:125], v[232:235], v[204:207], v[122:125]
	ds_read_b128 v[152:155], v144 offset:1024
	v_mfma_f32_16x16x32_bf16 v[118:121], v[232:235], v[208:211], v[118:121]
	ds_read_b128 v[156:159], v144 offset:2048
	v_mfma_f32_16x16x32_bf16 v[114:117], v[232:235], v[212:215], v[114:117]
	ds_read_b128 v[162:165], v144 offset:3072
	v_mfma_f32_16x16x32_bf16 v[110:113], v[232:235], v[216:219], v[110:113]
	ds_read_b128 v[166:169], v144 offset:4096
	v_mfma_f32_16x16x32_bf16 v[106:109], v[232:235], v[220:223], v[106:109]
	ds_read_b128 v[170:173], v144 offset:5120
	v_mfma_f32_16x16x32_bf16 v[102:105], v[232:235], v[224:227], v[102:105]
	ds_read_b128 v[176:179], v144 offset:6144
	v_mfma_f32_16x16x32_bf16 v[98:101], v[232:235], v[228:231], v[98:101]
	ds_read_b128 v[180:183], v144 offset:7168
	v_mfma_f32_16x16x32_bf16 v[94:97], v[236:239], v[200:203], v[94:97]
	v_add_u32_e32 v144, s40, v137
	v_mfma_f32_16x16x32_bf16 v[90:93], v[236:239], v[204:207], v[90:93]
	v_mfma_f32_16x16x32_bf16 v[86:89], v[236:239], v[208:211], v[86:89]
	ds_read_b128 v[184:187], v144 offset:16384
	v_mfma_f32_16x16x32_bf16 v[82:85], v[236:239], v[212:215], v[82:85]
	ds_read_b128 v[188:191], v144 offset:17408
	v_mfma_f32_16x16x32_bf16 v[78:81], v[236:239], v[216:219], v[78:81]
	ds_read_b128 v[192:195], v144 offset:18432
	v_mfma_f32_16x16x32_bf16 v[74:77], v[236:239], v[220:223], v[74:77]
	ds_read_b128 v[196:199], v144 offset:19456
	s_add_i32 s42, s46, s41
	v_mfma_f32_16x16x32_bf16 v[70:73], v[236:239], v[224:227], v[70:73]
	s_mov_b32 m0, s42
	v_lshl_add_u64 v[142:143], v[132:133], 0, s[2:3]
	v_mfma_f32_16x16x32_bf16 v[66:69], v[236:239], v[228:231], v[66:69]
	global_load_lds_dwordx4 v[132:133], off
	s_addk_i32 m0, 0x1000
	v_mfma_f32_16x16x32_bf16 v[62:65], v[240:243], v[200:203], v[62:65]
;     ...
;   __syncthreads();
;   G2_STAGE(0); G2_STAGE(1);
;   const int fsw = (0x78 >> (((r16 >> 2) & 3) * 2)) & 3;
;   const int aoff = (wm * 128 + r16) * 64 + ((quad ^ fsw) << 4);
;   const int boff = 16384 + (wn * 64 + r16) * 64 + ((quad ^ fsw) << 4);
;   for (int kt = 0; kt < nk; kt++) {
;     if (kt + 1 < nk) asm volatile("s_waitcnt vmcnt(6)" ::: "memory");
;     else asm volatile("s_waitcnt vmcnt(0)" ::: "memory");
;     __builtin_amdgcn_s_barrier();
;     asm volatile("" ::: "memory");
;     if (kt + 2 < nk) G2_STAGE(kt + 2);
;     const char* cS = smem + (kt % 3) * 24576;
;     bf16x8 xa[8], wb[4];
; #pragma unroll
;     for (int f = 0; f < 8; f++) xa[f] = *(const bf16x8*)(cS + aoff + f * 1024);
; #pragma unroll
;     for (int f = 0; f < 4; f++) wb[f] = *(const bf16x8*)(cS + boff + f * 1024);
; #pragma unroll
;     for (int nf = 0; nf < 4; nf++)
; #pragma unroll
;       for (int mf = 0; mf < 8; mf++)
;         acc[nf][mf] = __builtin_amdgcn_mfma_f32_16x16x32_bf16(wb[nf], xa[mf], acc[nf][mf], 0, 0, 0);
;   }
	v_mfma_f32_16x16x32_bf16 v[58:61], v[240:243], v[204:207], v[58:61]
	v_mfma_f32_16x16x32_bf16 v[54:57], v[240:243], v[208:211], v[54:57]
	global_load_lds_dwordx4 v[142:143], off
	v_lshl_add_u64 v[142:143], v[142:143], 0, s[2:3]
	s_addk_i32 m0, 0x1000
	v_mfma_f32_16x16x32_bf16 v[50:53], v[240:243], v[212:215], v[50:53]
	v_mfma_f32_16x16x32_bf16 v[46:49], v[240:243], v[216:219], v[46:49]
	v_mfma_f32_16x16x32_bf16 v[42:45], v[240:243], v[220:223], v[42:45]
	global_load_lds_dwordx4 v[142:143], off
	v_lshl_add_u64 v[142:143], v[142:143], 0, s[2:3]
	s_addk_i32 m0, 0x1000
	v_mfma_f32_16x16x32_bf16 v[38:41], v[240:243], v[224:227], v[38:41]
	v_mfma_f32_16x16x32_bf16 v[34:37], v[240:243], v[228:231], v[34:37]
	v_mfma_f32_16x16x32_bf16 v[30:33], v[244:247], v[200:203], v[30:33]
	global_load_lds_dwordx4 v[142:143], off
	s_addk_i32 m0, 0x1000
	v_lshl_add_u64 v[142:143], v[134:135], 0, s[2:3]
	v_mfma_f32_16x16x32_bf16 v[26:29], v[244:247], v[204:207], v[26:29]
	v_mfma_f32_16x16x32_bf16 v[22:25], v[244:247], v[208:211], v[22:25]
	v_mfma_f32_16x16x32_bf16 v[18:21], v[244:247], v[212:215], v[18:21]
	global_load_lds_dwordx4 v[134:135], off
	s_addk_i32 m0, 0x1000
	v_lshl_add_u64 v[132:133], v[132:133], 0, s[12:13]
	v_mfma_f32_16x16x32_bf16 v[14:17], v[244:247], v[216:219], v[14:17]
	v_mfma_f32_16x16x32_bf16 v[10:13], v[244:247], v[220:223], v[10:13]
	v_mfma_f32_16x16x32_bf16 v[6:9], v[244:247], v[224:227], v[6:9]
	global_load_lds_dwordx4 v[142:143], off
	v_lshl_add_u64 v[134:135], v[134:135], 0, s[4:5]
	v_mfma_f32_16x16x32_bf16 v[2:5], v[244:247], v[228:231], v[2:5]
	s_mov_b32 s41, s40
	s_add_i32 s40, s40, 0x6000
	s_cmp_eq_u32 s40, 0x12000
	s_cselect_b32 s40, 0, s40
	s_sub_i32 s39, s39, 1
	s_cmp_lg_u32 s39, 0
	s_cbranch_scc1 .Lt11_loop
	s_waitcnt vmcnt(6) lgkmcnt(0)
	s_barrier
	v_add_u32_e32 v144, s40, v136
	v_mfma_f32_16x16x32_bf16 v[126:129], v[184:187], v[146:149], v[126:129]
	ds_read_b128 v[200:203], v144 offset:0
	v_mfma_f32_16x16x32_bf16 v[122:125], v[184:187], v[152:155], v[122:125]
	ds_read_b128 v[204:207], v144 offset:1024
	v_mfma_f32_16x16x32_bf16 v[118:121], v[184:187], v[156:159], v[118:121]
	ds_read_b128 v[208:211], v144 offset:2048
	v_mfma_f32_16x16x32_bf16 v[114:117], v[184:187], v[162:165], v[114:117]
	ds_read_b128 v[212:215], v144 offset:3072
	v_mfma_f32_16x16x32_bf16 v[110:113], v[184:187], v[166:169], v[110:113]
	ds_read_b128 v[216:219], v144 offset:4096
	v_mfma_f32_16x16x32_bf16 v[106:109], v[184:187], v[170:173], v[106:109]
	ds_read_b128 v[220:223], v144 offset:5120
	v_mfma_f32_16x16x32_bf16 v[102:105], v[184:187], v[176:179], v[102:105]
	ds_read_b128 v[224:227], v144 offset:6144
	v_mfma_f32_16x16x32_bf16 v[98:101], v[184:187], v[180:183], v[98:101]
	ds_read_b128 v[228:231], v144 offset:7168
	v_mfma_f32_16x16x32_bf16 v[94:97], v[188:191], v[146:149], v[94:97]
	v_add_u32_e32 v144, s40, v137
	v_mfma_f32_16x16x32_bf16 v[90:93], v[188:191], v[152:155], v[90:93]
	v_mfma_f32_16x16x32_bf16 v[86:89], v[188:191], v[156:159], v[86:89]
	ds_read_b128 v[232:235], v144 offset:16384
	v_mfma_f32_16x16x32_bf16 v[82:85], v[188:191], v[162:165], v[82:85]
	ds_read_b128 v[236:239], v144 offset:17408
	v_mfma_f32_16x16x32_bf16 v[78:81], v[188:191], v[166:169], v[78:81]
	ds_read_b128 v[240:243], v144 offset:18432
	v_mfma_f32_16x16x32_bf16 v[74:77], v[188:191], v[170:173], v[74:77]
	ds_read_b128 v[244:247], v144 offset:19456
	s_add_i32 s42, s46, s41
	v_mfma_f32_16x16x32_bf16 v[70:73], v[188:191], v[176:179], v[70:73]
	s_mov_b32 m0, s42
	v_lshl_add_u64 v[142:143], v[132:133], 0, s[2:3]
	v_mfma_f32_16x16x32_bf16 v[66:69], v[188:191], v[180:183], v[66:69]
	global_load_lds_dwordx4 v[132:133], off
	s_addk_i32 m0, 0x1000
	v_mfma_f32_16x16x32_bf16 v[62:65], v[192:195], v[146:149], v[62:65]
	v_mfma_f32_16x16x32_bf16 v[58:61], v[192:195], v[152:155], v[58:61]
	v_mfma_f32_16x16x32_bf16 v[54:57], v[192:195], v[156:159], v[54:57]
	global_load_lds_dwordx4 v[142:143], off
	v_lshl_add_u64 v[142:143], v[142:143], 0, s[2:3]
	s_addk_i32 m0, 0x1000
	v_mfma_f32_16x16x32_bf16 v[50:53], v[192:195], v[162:165], v[50:53]
	v_mfma_f32_16x16x32_bf16 v[46:49], v[192:195], v[166:169], v[46:49]
	v_mfma_f32_16x16x32_bf16 v[42:45], v[192:195], v[170:173], v[42:45]
	global_load_lds_dwordx4 v[142:143], off
	v_lshl_add_u64 v[142:143], v[142:143], 0, s[2:3]
	s_addk_i32 m0, 0x1000
	v_mfma_f32_16x16x32_bf16 v[38:41], v[192:195], v[176:179], v[38:41]
	v_mfma_f32_16x16x32_bf16 v[34:37], v[192:195], v[180:183], v[34:37]
	v_mfma_f32_16x16x32_bf16 v[30:33], v[196:199], v[146:149], v[30:33]
	global_load_lds_dwordx4 v[142:143], off
	s_addk_i32 m0, 0x1000
	v_lshl_add_u64 v[142:143], v[134:135], 0, s[2:3]
	v_mfma_f32_16x16x32_bf16 v[26:29], v[196:199], v[152:155], v[26:29]
	v_mfma_f32_16x16x32_bf16 v[22:25], v[196:199], v[156:159], v[22:25]
	v_mfma_f32_16x16x32_bf16 v[18:21], v[196:199], v[162:165], v[18:21]
	global_load_lds_dwordx4 v[134:135], off
	s_addk_i32 m0, 0x1000
	v_lshl_add_u64 v[132:133], v[132:133], 0, s[12:13]
	v_mfma_f32_16x16x32_bf16 v[14:17], v[196:199], v[166:169], v[14:17]
	v_mfma_f32_16x16x32_bf16 v[10:13], v[196:199], v[170:173], v[10:13]
	v_mfma_f32_16x16x32_bf16 v[6:9], v[196:199], v[176:179], v[6:9]
	global_load_lds_dwordx4 v[142:143], off
	v_lshl_add_u64 v[134:135], v[134:135], 0, s[4:5]
	v_mfma_f32_16x16x32_bf16 v[2:5], v[196:199], v[180:183], v[2:5]
	s_mov_b32 s41, s40
	s_add_i32 s40, s40, 0x6000
	s_cmp_eq_u32 s40, 0x12000
	s_cselect_b32 s40, 0, s40
	s_waitcnt vmcnt(6) lgkmcnt(0)
	s_barrier
;     ...
;   for (int kt = 0; kt < nk; kt++) {
;     if (kt + 1 < nk) asm volatile("s_waitcnt vmcnt(6)" ::: "memory");
;     else asm volatile("s_waitcnt vmcnt(0)" ::: "memory");
;     __builtin_amdgcn_s_barrier();
;     asm volatile("" ::: "memory");
;     if (kt + 2 < nk) G2_STAGE(kt + 2);
;     const char* cS = smem + (kt % 3) * 24576;
;     bf16x8 xa[8], wb[4];
; #pragma unroll
;     for (int f = 0; f < 8; f++) xa[f] = *(const bf16x8*)(cS + aoff + f * 1024);
; #pragma unroll
;     for (int f = 0; f < 4; f++) wb[f] = *(const bf16x8*)(cS + boff + f * 1024);
; #pragma unroll
;     for (int nf = 0; nf < 4; nf++)
; #pragma unroll
;       for (int mf = 0; mf < 8; mf++)
;         acc[nf][mf] = __builtin_amdgcn_mfma_f32_16x16x32_bf16(wb[nf], xa[mf], acc[nf][mf], 0, 0, 0);
;   }
	v_add_u32_e32 v144, s40, v136
	v_mfma_f32_16x16x32_bf16 v[126:129], v[232:235], v[200:203], v[126:129]
	ds_read_b128 v[146:149], v144 offset:0
	v_mfma_f32_16x16x32_bf16 v[122:125], v[232:235], v[204:207], v[122:125]
	ds_read_b128 v[152:155], v144 offset:1024
	v_mfma_f32_16x16x32_bf16 v[118:121], v[232:235], v[208:211], v[118:121]
	ds_read_b128 v[156:159], v144 offset:2048
	v_mfma_f32_16x16x32_bf16 v[114:117], v[232:235], v[212:215], v[114:117]
	ds_read_b128 v[162:165], v144 offset:3072
	v_mfma_f32_16x16x32_bf16 v[110:113], v[232:235], v[216:219], v[110:113]
	ds_read_b128 v[166:169], v144 offset:4096
	v_mfma_f32_16x16x32_bf16 v[106:109], v[232:235], v[220:223], v[106:109]
	ds_read_b128 v[170:173], v144 offset:5120
	v_mfma_f32_16x16x32_bf16 v[102:105], v[232:235], v[224:227], v[102:105]
	ds_read_b128 v[176:179], v144 offset:6144
	v_mfma_f32_16x16x32_bf16 v[98:101], v[232:235], v[228:231], v[98:101]
	ds_read_b128 v[180:183], v144 offset:7168
	v_mfma_f32_16x16x32_bf16 v[94:97], v[236:239], v[200:203], v[94:97]
	v_add_u32_e32 v144, s40, v137
	v_mfma_f32_16x16x32_bf16 v[90:93], v[236:239], v[204:207], v[90:93]
	v_mfma_f32_16x16x32_bf16 v[86:89], v[236:239], v[208:211], v[86:89]
	ds_read_b128 v[184:187], v144 offset:16384
	v_mfma_f32_16x16x32_bf16 v[82:85], v[236:239], v[212:215], v[82:85]
	ds_read_b128 v[188:191], v144 offset:17408
	v_mfma_f32_16x16x32_bf16 v[78:81], v[236:239], v[216:219], v[78:81]
	ds_read_b128 v[192:195], v144 offset:18432
	v_mfma_f32_16x16x32_bf16 v[74:77], v[236:239], v[220:223], v[74:77]
	ds_read_b128 v[196:199], v144 offset:19456
	v_mfma_f32_16x16x32_bf16 v[70:73], v[236:239], v[224:227], v[70:73]
	v_mfma_f32_16x16x32_bf16 v[66:69], v[236:239], v[228:231], v[66:69]
	v_mfma_f32_16x16x32_bf16 v[62:65], v[240:243], v[200:203], v[62:65]
	v_mfma_f32_16x16x32_bf16 v[58:61], v[240:243], v[204:207], v[58:61]
	v_mfma_f32_16x16x32_bf16 v[54:57], v[240:243], v[208:211], v[54:57]
	v_mfma_f32_16x16x32_bf16 v[50:53], v[240:243], v[212:215], v[50:53]
	v_mfma_f32_16x16x32_bf16 v[46:49], v[240:243], v[216:219], v[46:49]
	v_mfma_f32_16x16x32_bf16 v[42:45], v[240:243], v[220:223], v[42:45]
	v_mfma_f32_16x16x32_bf16 v[38:41], v[240:243], v[224:227], v[38:41]
	v_mfma_f32_16x16x32_bf16 v[34:37], v[240:243], v[228:231], v[34:37]
	v_mfma_f32_16x16x32_bf16 v[30:33], v[244:247], v[200:203], v[30:33]
	v_mfma_f32_16x16x32_bf16 v[26:29], v[244:247], v[204:207], v[26:29]
	v_mfma_f32_16x16x32_bf16 v[22:25], v[244:247], v[208:211], v[22:25]
	v_mfma_f32_16x16x32_bf16 v[18:21], v[244:247], v[212:215], v[18:21]
	v_mfma_f32_16x16x32_bf16 v[14:17], v[244:247], v[216:219], v[14:17]
	v_mfma_f32_16x16x32_bf16 v[10:13], v[244:247], v[220:223], v[10:13]
	v_mfma_f32_16x16x32_bf16 v[6:9], v[244:247], v[224:227], v[6:9]
	v_mfma_f32_16x16x32_bf16 v[2:5], v[244:247], v[228:231], v[2:5]
	s_mov_b32 s41, s40
	s_add_i32 s40, s40, 0x6000
	s_cmp_eq_u32 s40, 0x12000
	s_cselect_b32 s40, 0, s40
	s_waitcnt vmcnt(0) lgkmcnt(0)
	s_barrier
	v_add_u32_e32 v144, s40, v136
	v_mfma_f32_16x16x32_bf16 v[126:129], v[184:187], v[146:149], v[126:129]
	ds_read_b128 v[200:203], v144 offset:0
	v_mfma_f32_16x16x32_bf16 v[122:125], v[184:187], v[152:155], v[122:125]
	ds_read_b128 v[204:207], v144 offset:1024
	v_mfma_f32_16x16x32_bf16 v[118:121], v[184:187], v[156:159], v[118:121]
	ds_read_b128 v[208:211], v144 offset:2048
	v_mfma_f32_16x16x32_bf16 v[114:117], v[184:187], v[162:165], v[114:117]
	ds_read_b128 v[212:215], v144 offset:3072
	v_mfma_f32_16x16x32_bf16 v[110:113], v[184:187], v[166:169], v[110:113]
	ds_read_b128 v[216:219], v144 offset:4096
	v_mfma_f32_16x16x32_bf16 v[106:109], v[184:187], v[170:173], v[106:109]
	ds_read_b128 v[220:223], v144 offset:5120
	v_mfma_f32_16x16x32_bf16 v[102:105], v[184:187], v[176:179], v[102:105]
	ds_read_b128 v[224:227], v144 offset:6144
	v_mfma_f32_16x16x32_bf16 v[98:101], v[184:187], v[180:183], v[98:101]
	ds_read_b128 v[228:231], v144 offset:7168
	v_mfma_f32_16x16x32_bf16 v[94:97], v[188:191], v[146:149], v[94:97]
	v_add_u32_e32 v144, s40, v137
	v_mfma_f32_16x16x32_bf16 v[90:93], v[188:191], v[152:155], v[90:93]
	v_mfma_f32_16x16x32_bf16 v[86:89], v[188:191], v[156:159], v[86:89]
	ds_read_b128 v[232:235], v144 offset:16384
	v_mfma_f32_16x16x32_bf16 v[82:85], v[188:191], v[162:165], v[82:85]
	ds_read_b128 v[236:239], v144 offset:17408
	v_mfma_f32_16x16x32_bf16 v[78:81], v[188:191], v[166:169], v[78:81]
	ds_read_b128 v[240:243], v144 offset:18432
	v_mfma_f32_16x16x32_bf16 v[74:77], v[188:191], v[170:173], v[74:77]
	ds_read_b128 v[244:247], v144 offset:19456
	v_mfma_f32_16x16x32_bf16 v[70:73], v[188:191], v[176:179], v[70:73]
	v_mfma_f32_16x16x32_bf16 v[66:69], v[188:191], v[180:183], v[66:69]
	v_mfma_f32_16x16x32_bf16 v[62:65], v[192:195], v[146:149], v[62:65]
	v_mfma_f32_16x16x32_bf16 v[58:61], v[192:195], v[152:155], v[58:61]
	v_mfma_f32_16x16x32_bf16 v[54:57], v[192:195], v[156:159], v[54:57]
	v_mfma_f32_16x16x32_bf16 v[50:53], v[192:195], v[162:165], v[50:53]
	v_mfma_f32_16x16x32_bf16 v[46:49], v[192:195], v[166:169], v[46:49]
	v_mfma_f32_16x16x32_bf16 v[42:45], v[192:195], v[170:173], v[42:45]
	v_mfma_f32_16x16x32_bf16 v[38:41], v[192:195], v[176:179], v[38:41]
	v_mfma_f32_16x16x32_bf16 v[34:37], v[192:195], v[180:183], v[34:37]
	v_mfma_f32_16x16x32_bf16 v[30:33], v[196:199], v[146:149], v[30:33]
	v_mfma_f32_16x16x32_bf16 v[26:29], v[196:199], v[152:155], v[26:29]
	v_mfma_f32_16x16x32_bf16 v[22:25], v[196:199], v[156:159], v[22:25]
	v_mfma_f32_16x16x32_bf16 v[18:21], v[196:199], v[162:165], v[18:21]
	v_mfma_f32_16x16x32_bf16 v[14:17], v[196:199], v[166:169], v[14:17]
	v_mfma_f32_16x16x32_bf16 v[10:13], v[196:199], v[170:173], v[10:13]
	v_mfma_f32_16x16x32_bf16 v[6:9], v[196:199], v[176:179], v[6:9]
	v_mfma_f32_16x16x32_bf16 v[2:5], v[196:199], v[180:183], v[2:5]
	s_mov_b32 s41, s40
	s_add_i32 s40, s40, 0x6000
	s_cmp_eq_u32 s40, 0x12000
	s_cselect_b32 s40, 0, s40
	s_mov_b32 s4, 0x8000
	s_mov_b32 s5, 0
	s_mov_b32 s10, 0x10000
	s_mov_b32 s11, 0
	s_mov_b32 s44, 0x3fd744fd
	s_waitcnt lgkmcnt(0)
; DEVI float blo(unsigned u) { return __uint_as_float(u << 16); }
; DEVI float bhi(unsigned u) { return __uint_as_float(u & 0xffff0000u); }
;     ...
;   for (int kt = 0; kt < nk; kt++) {
;     if (kt + 1 < nk) asm volatile("s_waitcnt vmcnt(6)" ::: "memory");
;     else asm volatile("s_waitcnt vmcnt(0)" ::: "memory");
;     __builtin_amdgcn_s_barrier();
;     asm volatile("" ::: "memory");
;     if (kt + 2 < nk) G2_STAGE(kt + 2);
;     const char* cS = smem + (kt % 3) * 24576;
;     bf16x8 xa[8], wb[4];
; #pragma unroll
;     for (int f = 0; f < 8; f++) xa[f] = *(const bf16x8*)(cS + aoff + f * 1024);
; #pragma unroll
;     for (int f = 0; f < 4; f++) wb[f] = *(const bf16x8*)(cS + boff + f * 1024);
; #pragma unroll
;     for (int nf = 0; nf < 4; nf++)
; #pragma unroll
;       for (int mf = 0; mf < 8; mf++)
;         acc[nf][mf] = __builtin_amdgcn_mfma_f32_16x16x32_bf16(wb[nf], xa[mf], acc[nf][mf], 0, 0, 0);
;   }
;     ...
; #pragma unroll
;       for (int nf = 0; nf < 4; nf++) {
;         const int col = n0 + wn * 64 + nf * 16 + quad * 4;
;         f32x4 a = acc[nf][mf];
;         if (EPI == EPI_RESID || EPI == EPI_RESID_ATOMIC) {
;           f32x4 x = a;
;           if (EPI == EPI_RESID || kpart == 0) {
;             const u32x2 xr = *(const u32x2*)((const u16*)(p.ws + WS_XB) + (size_t)row * 1024 + col);
;             x[0] += ALPHA * blo(xr[0]); x[1] += ALPHA * bhi(xr[0]); x[2] += ALPHA * blo(xr[1]); x[3] += ALPHA * bhi(xr[1]);
;           }
;           if (EPI == EPI_RESID) *(f32x4*)((float*)(p.ws + WS_XF) + (size_t)row * 1024 + col) = x;
;           else *(f32x4*)((float*)(p.ws + WS_SLAB) + ((size_t)kpart * 512 + (row - T_P)) * 1024 + col) = x;
	v_mfma_f32_16x16x32_bf16 v[126:129], v[232:235], v[200:203], v[126:129]
	v_mfma_f32_16x16x32_bf16 v[122:125], v[232:235], v[204:207], v[122:125]
	v_mfma_f32_16x16x32_bf16 v[118:121], v[232:235], v[208:211], v[118:121]
	v_mfma_f32_16x16x32_bf16 v[114:117], v[232:235], v[212:215], v[114:117]
	v_mfma_f32_16x16x32_bf16 v[110:113], v[232:235], v[216:219], v[110:113]
	global_load_dwordx4 v[146:149], v[138:139], off offset:0
	v_mfma_f32_16x16x32_bf16 v[106:109], v[232:235], v[220:223], v[106:109]
	v_mfma_f32_16x16x32_bf16 v[102:105], v[232:235], v[224:227], v[102:105]
	global_load_dwordx4 v[152:155], v[138:139], off offset:128
	v_mfma_f32_16x16x32_bf16 v[98:101], v[232:235], v[228:231], v[98:101]
	v_lshl_add_u64 v[138:139], v[138:139], 0, s[4:5]
	v_mfma_f32_16x16x32_bf16 v[94:97], v[236:239], v[200:203], v[94:97]
	global_load_dwordx4 v[156:159], v[138:139], off offset:0
	v_mfma_f32_16x16x32_bf16 v[90:93], v[236:239], v[204:207], v[90:93]
	v_mfma_f32_16x16x32_bf16 v[86:89], v[236:239], v[208:211], v[86:89]
	global_load_dwordx4 v[162:165], v[138:139], off offset:128
	v_mfma_f32_16x16x32_bf16 v[82:85], v[236:239], v[212:215], v[82:85]
	v_lshl_add_u64 v[138:139], v[138:139], 0, s[4:5]
	v_mfma_f32_16x16x32_bf16 v[78:81], v[236:239], v[216:219], v[78:81]
	global_load_dwordx4 v[166:169], v[138:139], off offset:0
	v_mfma_f32_16x16x32_bf16 v[74:77], v[236:239], v[220:223], v[74:77]
	v_mfma_f32_16x16x32_bf16 v[70:73], v[236:239], v[224:227], v[70:73]
	global_load_dwordx4 v[170:173], v[138:139], off offset:128
	v_mfma_f32_16x16x32_bf16 v[66:69], v[236:239], v[228:231], v[66:69]
	v_lshl_add_u64 v[138:139], v[138:139], 0, s[4:5]
	v_mfma_f32_16x16x32_bf16 v[62:65], v[240:243], v[200:203], v[62:65]
	global_load_dwordx4 v[176:179], v[138:139], off offset:0
	v_mfma_f32_16x16x32_bf16 v[58:61], v[240:243], v[204:207], v[58:61]
	v_mfma_f32_16x16x32_bf16 v[54:57], v[240:243], v[208:211], v[54:57]
	global_load_dwordx4 v[180:183], v[138:139], off offset:128
	v_mfma_f32_16x16x32_bf16 v[50:53], v[240:243], v[212:215], v[50:53]
	v_lshl_add_u64 v[138:139], v[138:139], 0, s[4:5]
	v_mfma_f32_16x16x32_bf16 v[46:49], v[240:243], v[216:219], v[46:49]
	global_load_dwordx4 v[184:187], v[138:139], off offset:0
	v_mfma_f32_16x16x32_bf16 v[42:45], v[240:243], v[220:223], v[42:45]
	v_mfma_f32_16x16x32_bf16 v[38:41], v[240:243], v[224:227], v[38:41]
	global_load_dwordx4 v[188:191], v[138:139], off offset:128
	v_mfma_f32_16x16x32_bf16 v[34:37], v[240:243], v[228:231], v[34:37]
	v_lshl_add_u64 v[138:139], v[138:139], 0, s[4:5]
	v_mfma_f32_16x16x32_bf16 v[30:33], v[244:247], v[200:203], v[30:33]
	global_load_dwordx4 v[192:195], v[138:139], off offset:0
	v_mfma_f32_16x16x32_bf16 v[26:29], v[244:247], v[204:207], v[26:29]
	v_mfma_f32_16x16x32_bf16 v[22:25], v[244:247], v[208:211], v[22:25]
	global_load_dwordx4 v[196:199], v[138:139], off offset:128
	v_mfma_f32_16x16x32_bf16 v[18:21], v[244:247], v[212:215], v[18:21]
	v_lshl_add_u64 v[138:139], v[138:139], 0, s[4:5]
	v_mfma_f32_16x16x32_bf16 v[14:17], v[244:247], v[216:219], v[14:17]
	v_mfma_f32_16x16x32_bf16 v[10:13], v[244:247], v[220:223], v[10:13]
	v_mfma_f32_16x16x32_bf16 v[6:9], v[244:247], v[224:227], v[6:9]
	v_mfma_f32_16x16x32_bf16 v[2:5], v[244:247], v[228:231], v[2:5]
	s_mov_b32 m0, s43
	global_load_dwordx4 v[200:203], v[138:139], off offset:0
	global_load_dwordx4 v[204:207], v[138:139], off offset:128
	v_lshl_add_u64 v[138:139], v[138:139], 0, s[4:5]
	global_load_dwordx4 v[208:211], v[138:139], off offset:0
	global_load_dwordx4 v[212:215], v[138:139], off offset:128
	v_lshl_add_u64 v[138:139], v[138:139], 0, s[4:5]
	s_nop 7
	s_waitcnt vmcnt(15)
	v_permlane16_swap_b32_e32 v146, v148
	v_permlane16_swap_b32_e32 v147, v149
	v_lshlrev_b32_e32 v216, 16, v146
	v_and_b32_e32 v146, 0xffff0000, v146
	v_lshlrev_b32_e32 v217, 16, v147
	v_and_b32_e32 v147, 0xffff0000, v147
	v_fmac_f32_e32 v126, s44, v216
	v_fmac_f32_e32 v127, s44, v146
	v_fmac_f32_e32 v128, s44, v217
	v_fmac_f32_e32 v129, s44, v147
	global_store_dwordx4 v[140:141], v[126:129], off offset:0
	v_lshlrev_b32_e32 v216, 16, v148
	v_and_b32_e32 v148, 0xffff0000, v148
	v_lshlrev_b32_e32 v217, 16, v149
	v_and_b32_e32 v149, 0xffff0000, v149
	v_fmac_f32_e32 v94, s44, v216
	v_fmac_f32_e32 v95, s44, v148
	v_fmac_f32_e32 v96, s44, v217
	v_fmac_f32_e32 v97, s44, v149
	global_store_dwordx4 v[140:141], v[94:97], off offset:64
	s_waitcnt vmcnt(16)
	v_permlane16_swap_b32_e32 v152, v154
	v_permlane16_swap_b32_e32 v153, v155
	v_lshlrev_b32_e32 v216, 16, v152
	v_and_b32_e32 v152, 0xffff0000, v152
	v_lshlrev_b32_e32 v217, 16, v153
	v_and_b32_e32 v153, 0xffff0000, v153
	v_fmac_f32_e32 v62, s44, v216
	v_fmac_f32_e32 v63, s44, v152
	v_fmac_f32_e32 v64, s44, v217
	v_fmac_f32_e32 v65, s44, v153
	global_store_dwordx4 v[140:141], v[62:65], off offset:128
	v_lshlrev_b32_e32 v216, 16, v154
	v_and_b32_e32 v154, 0xffff0000, v154
	v_lshlrev_b32_e32 v217, 16, v155
	v_and_b32_e32 v155, 0xffff0000, v155
	v_fmac_f32_e32 v30, s44, v216
	v_fmac_f32_e32 v31, s44, v154
	v_fmac_f32_e32 v32, s44, v217
	v_fmac_f32_e32 v33, s44, v155
	global_store_dwordx4 v[140:141], v[30:33], off offset:192
	v_lshl_add_u64 v[140:141], v[140:141], 0, s[10:11]
	s_waitcnt vmcnt(17)
	v_permlane16_swap_b32_e32 v156, v158
	v_permlane16_swap_b32_e32 v157, v159
	v_lshlrev_b32_e32 v216, 16, v156
	v_and_b32_e32 v156, 0xffff0000, v156
	v_lshlrev_b32_e32 v217, 16, v157
	v_and_b32_e32 v157, 0xffff0000, v157
	v_fmac_f32_e32 v122, s44, v216
	v_fmac_f32_e32 v123, s44, v156
	v_fmac_f32_e32 v124, s44, v217
	v_fmac_f32_e32 v125, s44, v157
	global_store_dwordx4 v[140:141], v[122:125], off offset:0
	v_lshlrev_b32_e32 v216, 16, v158
	v_and_b32_e32 v158, 0xffff0000, v158
	v_lshlrev_b32_e32 v217, 16, v159
	v_and_b32_e32 v159, 0xffff0000, v159
	v_fmac_f32_e32 v90, s44, v216
	v_fmac_f32_e32 v91, s44, v158
	v_fmac_f32_e32 v92, s44, v217
	v_fmac_f32_e32 v93, s44, v159
	global_store_dwordx4 v[140:141], v[90:93], off offset:64
	s_waitcnt vmcnt(18)
; DEVI float blo(unsigned u) { return __uint_as_float(u << 16); }
; DEVI float bhi(unsigned u) { return __uint_as_float(u & 0xffff0000u); }
;     ...
; #pragma unroll
;       for (int nf = 0; nf < 4; nf++) {
;         const int col = n0 + wn * 64 + nf * 16 + quad * 4;
;         f32x4 a = acc[nf][mf];
;         if (EPI == EPI_RESID || EPI == EPI_RESID_ATOMIC) {
;           f32x4 x = a;
;           if (EPI == EPI_RESID || kpart == 0) {
;             const u32x2 xr = *(const u32x2*)((const u16*)(p.ws + WS_XB) + (size_t)row * 1024 + col);
;             x[0] += ALPHA * blo(xr[0]); x[1] += ALPHA * bhi(xr[0]); x[2] += ALPHA * blo(xr[1]); x[3] += ALPHA * bhi(xr[1]);
;           }
;           if (EPI == EPI_RESID) *(f32x4*)((float*)(p.ws + WS_XF) + (size_t)row * 1024 + col) = x;
;           else *(f32x4*)((float*)(p.ws + WS_SLAB) + ((size_t)kpart * 512 + (row - T_P)) * 1024 + col) = x;
	v_permlane16_swap_b32_e32 v162, v164
	v_permlane16_swap_b32_e32 v163, v165
	v_lshlrev_b32_e32 v216, 16, v162
	v_and_b32_e32 v162, 0xffff0000, v162
	v_lshlrev_b32_e32 v217, 16, v163
	v_and_b32_e32 v163, 0xffff0000, v163
	v_fmac_f32_e32 v58, s44, v216
	v_fmac_f32_e32 v59, s44, v162
	v_fmac_f32_e32 v60, s44, v217
	v_fmac_f32_e32 v61, s44, v163
	global_store_dwordx4 v[140:141], v[58:61], off offset:128
	v_lshlrev_b32_e32 v216, 16, v164
	v_and_b32_e32 v164, 0xffff0000, v164
	v_lshlrev_b32_e32 v217, 16, v165
	v_and_b32_e32 v165, 0xffff0000, v165
	v_fmac_f32_e32 v26, s44, v216
	v_fmac_f32_e32 v27, s44, v164
	v_fmac_f32_e32 v28, s44, v217
	v_fmac_f32_e32 v29, s44, v165
	global_store_dwordx4 v[140:141], v[26:29], off offset:192
	v_lshl_add_u64 v[140:141], v[140:141], 0, s[10:11]
	s_waitcnt vmcnt(19)
	v_permlane16_swap_b32_e32 v166, v168
	v_permlane16_swap_b32_e32 v167, v169
	v_lshlrev_b32_e32 v216, 16, v166
	v_and_b32_e32 v166, 0xffff0000, v166
	v_lshlrev_b32_e32 v217, 16, v167
	v_and_b32_e32 v167, 0xffff0000, v167
	v_fmac_f32_e32 v118, s44, v216
	v_fmac_f32_e32 v119, s44, v166
	v_fmac_f32_e32 v120, s44, v217
	v_fmac_f32_e32 v121, s44, v167
	global_store_dwordx4 v[140:141], v[118:121], off offset:0
	v_lshlrev_b32_e32 v216, 16, v168
	v_and_b32_e32 v168, 0xffff0000, v168
	v_lshlrev_b32_e32 v217, 16, v169
	v_and_b32_e32 v169, 0xffff0000, v169
	v_fmac_f32_e32 v86, s44, v216
	v_fmac_f32_e32 v87, s44, v168
	v_fmac_f32_e32 v88, s44, v217
	v_fmac_f32_e32 v89, s44, v169
	global_store_dwordx4 v[140:141], v[86:89], off offset:64
	s_waitcnt vmcnt(20)
	v_permlane16_swap_b32_e32 v170, v172
	v_permlane16_swap_b32_e32 v171, v173
	v_lshlrev_b32_e32 v216, 16, v170
	v_and_b32_e32 v170, 0xffff0000, v170
	v_lshlrev_b32_e32 v217, 16, v171
	v_and_b32_e32 v171, 0xffff0000, v171
	v_fmac_f32_e32 v54, s44, v216
	v_fmac_f32_e32 v55, s44, v170
	v_fmac_f32_e32 v56, s44, v217
	v_fmac_f32_e32 v57, s44, v171
	global_store_dwordx4 v[140:141], v[54:57], off offset:128
	v_lshlrev_b32_e32 v216, 16, v172
	v_and_b32_e32 v172, 0xffff0000, v172
	v_lshlrev_b32_e32 v217, 16, v173
	v_and_b32_e32 v173, 0xffff0000, v173
	v_fmac_f32_e32 v22, s44, v216
	v_fmac_f32_e32 v23, s44, v172
	v_fmac_f32_e32 v24, s44, v217
	v_fmac_f32_e32 v25, s44, v173
	global_store_dwordx4 v[140:141], v[22:25], off offset:192
	v_lshl_add_u64 v[140:141], v[140:141], 0, s[10:11]
	s_waitcnt vmcnt(21)
	v_permlane16_swap_b32_e32 v176, v178
	v_permlane16_swap_b32_e32 v177, v179
	v_lshlrev_b32_e32 v216, 16, v176
	v_and_b32_e32 v176, 0xffff0000, v176
	v_lshlrev_b32_e32 v217, 16, v177
	v_and_b32_e32 v177, 0xffff0000, v177
	v_fmac_f32_e32 v114, s44, v216
	v_fmac_f32_e32 v115, s44, v176
	v_fmac_f32_e32 v116, s44, v217
	v_fmac_f32_e32 v117, s44, v177
	global_store_dwordx4 v[140:141], v[114:117], off offset:0
	v_lshlrev_b32_e32 v216, 16, v178
	v_and_b32_e32 v178, 0xffff0000, v178
	v_lshlrev_b32_e32 v217, 16, v179
	v_and_b32_e32 v179, 0xffff0000, v179
	v_fmac_f32_e32 v82, s44, v216
	v_fmac_f32_e32 v83, s44, v178
	v_fmac_f32_e32 v84, s44, v217
	v_fmac_f32_e32 v85, s44, v179
	global_store_dwordx4 v[140:141], v[82:85], off offset:64
	s_waitcnt vmcnt(22)
	v_permlane16_swap_b32_e32 v180, v182
	v_permlane16_swap_b32_e32 v181, v183
	v_lshlrev_b32_e32 v216, 16, v180
	v_and_b32_e32 v180, 0xffff0000, v180
	v_lshlrev_b32_e32 v217, 16, v181
	v_and_b32_e32 v181, 0xffff0000, v181
	v_fmac_f32_e32 v50, s44, v216
	v_fmac_f32_e32 v51, s44, v180
	v_fmac_f32_e32 v52, s44, v217
	v_fmac_f32_e32 v53, s44, v181
	global_store_dwordx4 v[140:141], v[50:53], off offset:128
	v_lshlrev_b32_e32 v216, 16, v182
	v_and_b32_e32 v182, 0xffff0000, v182
	v_lshlrev_b32_e32 v217, 16, v183
	v_and_b32_e32 v183, 0xffff0000, v183
	v_fmac_f32_e32 v18, s44, v216
	v_fmac_f32_e32 v19, s44, v182
	v_fmac_f32_e32 v20, s44, v217
	v_fmac_f32_e32 v21, s44, v183
	global_store_dwordx4 v[140:141], v[18:21], off offset:192
	v_lshl_add_u64 v[140:141], v[140:141], 0, s[10:11]
	s_waitcnt vmcnt(23)
	v_permlane16_swap_b32_e32 v184, v186
	v_permlane16_swap_b32_e32 v185, v187
	v_lshlrev_b32_e32 v216, 16, v184
	v_and_b32_e32 v184, 0xffff0000, v184
	v_lshlrev_b32_e32 v217, 16, v185
	v_and_b32_e32 v185, 0xffff0000, v185
	v_fmac_f32_e32 v110, s44, v216
	v_fmac_f32_e32 v111, s44, v184
	v_fmac_f32_e32 v112, s44, v217
	v_fmac_f32_e32 v113, s44, v185
	global_store_dwordx4 v[140:141], v[110:113], off offset:0
	v_lshlrev_b32_e32 v216, 16, v186
	v_and_b32_e32 v186, 0xffff0000, v186
	v_lshlrev_b32_e32 v217, 16, v187
	v_and_b32_e32 v187, 0xffff0000, v187
	v_fmac_f32_e32 v78, s44, v216
	v_fmac_f32_e32 v79, s44, v186
	v_fmac_f32_e32 v80, s44, v217
	v_fmac_f32_e32 v81, s44, v187
	global_store_dwordx4 v[140:141], v[78:81], off offset:64
	s_waitcnt vmcnt(24)
	v_permlane16_swap_b32_e32 v188, v190
	v_permlane16_swap_b32_e32 v189, v191
	v_lshlrev_b32_e32 v216, 16, v188
	v_and_b32_e32 v188, 0xffff0000, v188
	v_lshlrev_b32_e32 v217, 16, v189
	v_and_b32_e32 v189, 0xffff0000, v189
	v_fmac_f32_e32 v46, s44, v216
	v_fmac_f32_e32 v47, s44, v188
	v_fmac_f32_e32 v48, s44, v217
	v_fmac_f32_e32 v49, s44, v189
	global_store_dwordx4 v[140:141], v[46:49], off offset:128
	v_lshlrev_b32_e32 v216, 16, v190
	v_and_b32_e32 v190, 0xffff0000, v190
	v_lshlrev_b32_e32 v217, 16, v191
	v_and_b32_e32 v191, 0xffff0000, v191
	v_fmac_f32_e32 v14, s44, v216
	v_fmac_f32_e32 v15, s44, v190
	v_fmac_f32_e32 v16, s44, v217
	v_fmac_f32_e32 v17, s44, v191
	global_store_dwordx4 v[140:141], v[14:17], off offset:192
	v_lshl_add_u64 v[140:141], v[140:141], 0, s[10:11]
	s_waitcnt vmcnt(25)
; DEVI float blo(unsigned u) { return __uint_as_float(u << 16); }
; DEVI float bhi(unsigned u) { return __uint_as_float(u & 0xffff0000u); }
; DEVI int xcd_first_tile() { return (blockIdx.x & 7) * (gridDim.x >> 3) + (blockIdx.x >> 3); }
;     ...
; #pragma unroll
;       for (int nf = 0; nf < 4; nf++) {
;         const int col = n0 + wn * 64 + nf * 16 + quad * 4;
;         f32x4 a = acc[nf][mf];
;         if (EPI == EPI_RESID || EPI == EPI_RESID_ATOMIC) {
;           f32x4 x = a;
;           if (EPI == EPI_RESID || kpart == 0) {
;             const u32x2 xr = *(const u32x2*)((const u16*)(p.ws + WS_XB) + (size_t)row * 1024 + col);
;             x[0] += ALPHA * blo(xr[0]); x[1] += ALPHA * bhi(xr[0]); x[2] += ALPHA * blo(xr[1]); x[3] += ALPHA * bhi(xr[1]);
;           }
;           if (EPI == EPI_RESID) *(f32x4*)((float*)(p.ws + WS_XF) + (size_t)row * 1024 + col) = x;
;           else *(f32x4*)((float*)(p.ws + WS_SLAB) + ((size_t)kpart * 512 + (row - T_P)) * 1024 + col) = x;
; DEVI void run_phase(const Params& p, int ph, char* smem) {
;     ...
;       for (int t = xcd_first_tile(); t < 512 + 16 * 11; t += xcd_tile_step()) {
;         if (t < 512) {
;           int mt_, nt_; tile_coords(t, 64, 8, mt_, nt_);
;           gemm_tile256<EPI_RESID>(p, hb, DFF, Bt, DFF, mt_ * 256, nt_ * 128, nullptr, 0, smem);
;         } else {
;           const int u_ = t - 512, tl_ = u_ / 11, q_ = u_ - tl_ * 11;
;           gemm_tile256<EPI_RESID_ATOMIC>(p, hb, DFF, Bt, DFF, (64 + (tl_ & 1)) * 256, (tl_ >> 1) * 128, nullptr, 0, smem, q_ * 256, 8, q_);
;         }
	v_permlane16_swap_b32_e32 v192, v194
	v_permlane16_swap_b32_e32 v193, v195
	v_lshlrev_b32_e32 v216, 16, v192
	v_and_b32_e32 v192, 0xffff0000, v192
	v_lshlrev_b32_e32 v217, 16, v193
	v_and_b32_e32 v193, 0xffff0000, v193
	v_fmac_f32_e32 v106, s44, v216
	v_fmac_f32_e32 v107, s44, v192
	v_fmac_f32_e32 v108, s44, v217
	v_fmac_f32_e32 v109, s44, v193
	global_store_dwordx4 v[140:141], v[106:109], off offset:0
	v_lshlrev_b32_e32 v216, 16, v194
	v_and_b32_e32 v194, 0xffff0000, v194
	v_lshlrev_b32_e32 v217, 16, v195
	v_and_b32_e32 v195, 0xffff0000, v195
	v_fmac_f32_e32 v74, s44, v216
	v_fmac_f32_e32 v75, s44, v194
	v_fmac_f32_e32 v76, s44, v217
	v_fmac_f32_e32 v77, s44, v195
	global_store_dwordx4 v[140:141], v[74:77], off offset:64
	s_waitcnt vmcnt(26)
	v_permlane16_swap_b32_e32 v196, v198
	v_permlane16_swap_b32_e32 v197, v199
	v_lshlrev_b32_e32 v216, 16, v196
	v_and_b32_e32 v196, 0xffff0000, v196
	v_lshlrev_b32_e32 v217, 16, v197
	v_and_b32_e32 v197, 0xffff0000, v197
	v_fmac_f32_e32 v42, s44, v216
	v_fmac_f32_e32 v43, s44, v196
	v_fmac_f32_e32 v44, s44, v217
	v_fmac_f32_e32 v45, s44, v197
	global_store_dwordx4 v[140:141], v[42:45], off offset:128
	v_lshlrev_b32_e32 v216, 16, v198
	v_and_b32_e32 v198, 0xffff0000, v198
	v_lshlrev_b32_e32 v217, 16, v199
	v_and_b32_e32 v199, 0xffff0000, v199
	v_fmac_f32_e32 v10, s44, v216
	v_fmac_f32_e32 v11, s44, v198
	v_fmac_f32_e32 v12, s44, v217
	v_fmac_f32_e32 v13, s44, v199
	global_store_dwordx4 v[140:141], v[10:13], off offset:192
	v_lshl_add_u64 v[140:141], v[140:141], 0, s[10:11]
	s_waitcnt vmcnt(27)
	v_permlane16_swap_b32_e32 v200, v202
	v_permlane16_swap_b32_e32 v201, v203
	v_lshlrev_b32_e32 v216, 16, v200
	v_and_b32_e32 v200, 0xffff0000, v200
	v_lshlrev_b32_e32 v217, 16, v201
	v_and_b32_e32 v201, 0xffff0000, v201
	v_fmac_f32_e32 v102, s44, v216
	v_fmac_f32_e32 v103, s44, v200
	v_fmac_f32_e32 v104, s44, v217
	v_fmac_f32_e32 v105, s44, v201
	global_store_dwordx4 v[140:141], v[102:105], off offset:0
	v_lshlrev_b32_e32 v216, 16, v202
	v_and_b32_e32 v202, 0xffff0000, v202
	v_lshlrev_b32_e32 v217, 16, v203
	v_and_b32_e32 v203, 0xffff0000, v203
	v_fmac_f32_e32 v70, s44, v216
	v_fmac_f32_e32 v71, s44, v202
	v_fmac_f32_e32 v72, s44, v217
	v_fmac_f32_e32 v73, s44, v203
	global_store_dwordx4 v[140:141], v[70:73], off offset:64
	s_waitcnt vmcnt(28)
	v_permlane16_swap_b32_e32 v204, v206
	v_permlane16_swap_b32_e32 v205, v207
	v_lshlrev_b32_e32 v216, 16, v204
	v_and_b32_e32 v204, 0xffff0000, v204
	v_lshlrev_b32_e32 v217, 16, v205
	v_and_b32_e32 v205, 0xffff0000, v205
	v_fmac_f32_e32 v38, s44, v216
	v_fmac_f32_e32 v39, s44, v204
	v_fmac_f32_e32 v40, s44, v217
	v_fmac_f32_e32 v41, s44, v205
	global_store_dwordx4 v[140:141], v[38:41], off offset:128
	v_lshlrev_b32_e32 v216, 16, v206
	v_and_b32_e32 v206, 0xffff0000, v206
	v_lshlrev_b32_e32 v217, 16, v207
	v_and_b32_e32 v207, 0xffff0000, v207
	v_fmac_f32_e32 v6, s44, v216
	v_fmac_f32_e32 v7, s44, v206
	v_fmac_f32_e32 v8, s44, v217
	v_fmac_f32_e32 v9, s44, v207
	global_store_dwordx4 v[140:141], v[6:9], off offset:192
	v_lshl_add_u64 v[140:141], v[140:141], 0, s[10:11]
	s_waitcnt vmcnt(29)
	v_permlane16_swap_b32_e32 v208, v210
	v_permlane16_swap_b32_e32 v209, v211
	v_lshlrev_b32_e32 v216, 16, v208
	v_and_b32_e32 v208, 0xffff0000, v208
	v_lshlrev_b32_e32 v217, 16, v209
	v_and_b32_e32 v209, 0xffff0000, v209
	v_fmac_f32_e32 v98, s44, v216
	v_fmac_f32_e32 v99, s44, v208
	v_fmac_f32_e32 v100, s44, v217
	v_fmac_f32_e32 v101, s44, v209
	global_store_dwordx4 v[140:141], v[98:101], off offset:0
	v_lshlrev_b32_e32 v216, 16, v210
	v_and_b32_e32 v210, 0xffff0000, v210
	v_lshlrev_b32_e32 v217, 16, v211
	v_and_b32_e32 v211, 0xffff0000, v211
	v_fmac_f32_e32 v66, s44, v216
	v_fmac_f32_e32 v67, s44, v210
	v_fmac_f32_e32 v68, s44, v217
	v_fmac_f32_e32 v69, s44, v211
	global_store_dwordx4 v[140:141], v[66:69], off offset:64
	s_waitcnt vmcnt(30)
	v_permlane16_swap_b32_e32 v212, v214
	v_permlane16_swap_b32_e32 v213, v215
	v_lshlrev_b32_e32 v216, 16, v212
	v_and_b32_e32 v212, 0xffff0000, v212
	v_lshlrev_b32_e32 v217, 16, v213
	v_and_b32_e32 v213, 0xffff0000, v213
	v_fmac_f32_e32 v34, s44, v216
	v_fmac_f32_e32 v35, s44, v212
	v_fmac_f32_e32 v36, s44, v217
	v_fmac_f32_e32 v37, s44, v213
	global_store_dwordx4 v[140:141], v[34:37], off offset:128
	v_lshlrev_b32_e32 v216, 16, v214
	v_and_b32_e32 v214, 0xffff0000, v214
	v_lshlrev_b32_e32 v217, 16, v215
	v_and_b32_e32 v215, 0xffff0000, v215
	v_fmac_f32_e32 v2, s44, v216
	v_fmac_f32_e32 v3, s44, v214
	v_fmac_f32_e32 v4, s44, v217
	v_fmac_f32_e32 v5, s44, v215
	global_store_dwordx4 v[140:141], v[2:5], off offset:192
	v_readlane_b32 s39, v250, 7
	s_cmpk_lg_u32 s39, 0x200
	s_cbranch_scc1 .LBB0_41
	v_readlane_b32 s40, v250, 0
	s_lshr_b32 s41, s40, 3
	s_and_b32 s40, s40, 7
	s_mul_i32 s40, s40, 22
	s_add_i32 s40, s40, s41
	s_cmp_lt_u32 s41, 22
	s_cselect_b32 s38, s40, 0x4000
	s_branch .LBB0_41

;     ...
;   __syncthreads();
;   G2_STAGE(0); G2_STAGE(1);
;   const int fsw = (0x78 >> (((r16 >> 2) & 3) * 2)) & 3;
;   const int aoff = (wm * 128 + r16) * 64 + ((quad ^ fsw) << 4);
;   const int boff = 16384 + (wn * 64 + r16) * 64 + ((quad ^ fsw) << 4);
;   for (int kt = 0; kt < nk; kt++) {
;     if (kt + 1 < nk) asm volatile("s_waitcnt vmcnt(6)" ::: "memory");
;     else asm volatile("s_waitcnt vmcnt(0)" ::: "memory");
;     __builtin_amdgcn_s_barrier();
;     asm volatile("" ::: "memory");
;     if (kt + 2 < nk) G2_STAGE(kt + 2);
;     const char* cS = smem + (kt % 3) * 24576;
;     bf16x8 xa[8], wb[4];
; #pragma unroll
;     for (int f = 0; f < 8; f++) xa[f] = *(const bf16x8*)(cS + aoff + f * 1024);
; #pragma unroll
;     for (int f = 0; f < 4; f++) wb[f] = *(const bf16x8*)(cS + boff + f * 1024);
; #pragma unroll
;     for (int nf = 0; nf < 4; nf++)
; #pragma unroll
;       for (int mf = 0; mf < 8; mf++)
;         acc[nf][mf] = __builtin_amdgcn_mfma_f32_16x16x32_bf16(wb[nf], xa[mf], acc[nf][mf], 0, 0, 0);
;   }
.Lt8_loop:
	s_waitcnt vmcnt(6) lgkmcnt(0)
	s_barrier
	v_add_u32_e32 v144, s40, v136
	v_mfma_f32_16x16x32_bf16 v[126:129], v[184:187], v[146:149], v[126:129]
	ds_read_b128 v[200:203], v144 offset:0
	v_mfma_f32_16x16x32_bf16 v[122:125], v[184:187], v[152:155], v[122:125]
	ds_read_b128 v[204:207], v144 offset:1024
	v_mfma_f32_16x16x32_bf16 v[118:121], v[184:187], v[156:159], v[118:121]
	ds_read_b128 v[208:211], v144 offset:2048
	v_mfma_f32_16x16x32_bf16 v[114:117], v[184:187], v[162:165], v[114:117]
	ds_read_b128 v[212:215], v144 offset:3072
	v_mfma_f32_16x16x32_bf16 v[110:113], v[184:187], v[166:169], v[110:113]
	ds_read_b128 v[216:219], v144 offset:4096
	v_mfma_f32_16x16x32_bf16 v[106:109], v[184:187], v[170:173], v[106:109]
	ds_read_b128 v[220:223], v144 offset:5120
	v_mfma_f32_16x16x32_bf16 v[102:105], v[184:187], v[176:179], v[102:105]
	ds_read_b128 v[224:227], v144 offset:6144
	v_mfma_f32_16x16x32_bf16 v[98:101], v[184:187], v[180:183], v[98:101]
	ds_read_b128 v[228:231], v144 offset:7168
	v_mfma_f32_16x16x32_bf16 v[94:97], v[188:191], v[146:149], v[94:97]
	v_add_u32_e32 v144, s40, v137
	v_mfma_f32_16x16x32_bf16 v[90:93], v[188:191], v[152:155], v[90:93]
	v_mfma_f32_16x16x32_bf16 v[86:89], v[188:191], v[156:159], v[86:89]
	ds_read_b128 v[232:235], v144 offset:16384
	v_mfma_f32_16x16x32_bf16 v[82:85], v[188:191], v[162:165], v[82:85]
	ds_read_b128 v[236:239], v144 offset:17408
	v_mfma_f32_16x16x32_bf16 v[78:81], v[188:191], v[166:169], v[78:81]
	ds_read_b128 v[240:243], v144 offset:18432
	v_mfma_f32_16x16x32_bf16 v[74:77], v[188:191], v[170:173], v[74:77]
	ds_read_b128 v[244:247], v144 offset:19456
	s_add_i32 s42, s46, s41
	v_mfma_f32_16x16x32_bf16 v[70:73], v[188:191], v[176:179], v[70:73]
	s_mov_b32 m0, s42
	v_lshl_add_u64 v[142:143], v[132:133], 0, s[2:3]
	v_mfma_f32_16x16x32_bf16 v[66:69], v[188:191], v[180:183], v[66:69]
	global_load_lds_dwordx4 v[132:133], off
	s_addk_i32 m0, 0x1000
	v_mfma_f32_16x16x32_bf16 v[62:65], v[192:195], v[146:149], v[62:65]
	v_mfma_f32_16x16x32_bf16 v[58:61], v[192:195], v[152:155], v[58:61]
	v_mfma_f32_16x16x32_bf16 v[54:57], v[192:195], v[156:159], v[54:57]
	global_load_lds_dwordx4 v[142:143], off
	v_lshl_add_u64 v[142:143], v[142:143], 0, s[2:3]
	s_addk_i32 m0, 0x1000
	v_mfma_f32_16x16x32_bf16 v[50:53], v[192:195], v[162:165], v[50:53]
	v_mfma_f32_16x16x32_bf16 v[46:49], v[192:195], v[166:169], v[46:49]
	v_mfma_f32_16x16x32_bf16 v[42:45], v[192:195], v[170:173], v[42:45]
	global_load_lds_dwordx4 v[142:143], off
	v_lshl_add_u64 v[142:143], v[142:143], 0, s[2:3]
	s_addk_i32 m0, 0x1000
	v_mfma_f32_16x16x32_bf16 v[38:41], v[192:195], v[176:179], v[38:41]
	v_mfma_f32_16x16x32_bf16 v[34:37], v[192:195], v[180:183], v[34:37]
	v_mfma_f32_16x16x32_bf16 v[30:33], v[196:199], v[146:149], v[30:33]
	global_load_lds_dwordx4 v[142:143], off
	s_addk_i32 m0, 0x1000
	v_lshl_add_u64 v[142:143], v[134:135], 0, s[2:3]
	v_mfma_f32_16x16x32_bf16 v[26:29], v[196:199], v[152:155], v[26:29]
	v_mfma_f32_16x16x32_bf16 v[22:25], v[196:199], v[156:159], v[22:25]
	v_mfma_f32_16x16x32_bf16 v[18:21], v[196:199], v[162:165], v[18:21]
	global_load_lds_dwordx4 v[134:135], off
	s_addk_i32 m0, 0x1000
	v_lshl_add_u64 v[132:133], v[132:133], 0, s[12:13]
	v_mfma_f32_16x16x32_bf16 v[14:17], v[196:199], v[166:169], v[14:17]
	v_mfma_f32_16x16x32_bf16 v[10:13], v[196:199], v[170:173], v[10:13]
	v_mfma_f32_16x16x32_bf16 v[6:9], v[196:199], v[176:179], v[6:9]
	global_load_lds_dwordx4 v[142:143], off
	v_lshl_add_u64 v[134:135], v[134:135], 0, s[4:5]
	v_mfma_f32_16x16x32_bf16 v[2:5], v[196:199], v[180:183], v[2:5]
	s_mov_b32 s41, s40
	s_add_i32 s40, s40, 0x6000
	s_cmp_eq_u32 s40, 0x12000
	s_cselect_b32 s40, 0, s40
	s_waitcnt vmcnt(6) lgkmcnt(0)
	s_barrier
	v_add_u32_e32 v144, s40, v136
	v_mfma_f32_16x16x32_bf16 v[126:129], v[232:235], v[200:203], v[126:129]
	ds_read_b128 v[146:149], v144 offset:0
	v_mfma_f32_16x16x32_bf16 v[122:125], v[232:235], v[204:207], v[122:125]
	ds_read_b128 v[152:155], v144 offset:1024
	v_mfma_f32_16x16x32_bf16 v[118:121], v[232:235], v[208:211], v[118:121]
	ds_read_b128 v[156:159], v144 offset:2048
	v_mfma_f32_16x16x32_bf16 v[114:117], v[232:235], v[212:215], v[114:117]
	ds_read_b128 v[162:165], v144 offset:3072
	v_mfma_f32_16x16x32_bf16 v[110:113], v[232:235], v[216:219], v[110:113]
	ds_read_b128 v[166:169], v144 offset:4096
	v_mfma_f32_16x16x32_bf16 v[106:109], v[232:235], v[220:223], v[106:109]
	ds_read_b128 v[170:173], v144 offset:5120
	v_mfma_f32_16x16x32_bf16 v[102:105], v[232:235], v[224:227], v[102:105]
	ds_read_b128 v[176:179], v144 offset:6144
	v_mfma_f32_16x16x32_bf16 v[98:101], v[232:235], v[228:231], v[98:101]
	ds_read_b128 v[180:183], v144 offset:7168
	v_mfma_f32_16x16x32_bf16 v[94:97], v[236:239], v[200:203], v[94:97]
	v_add_u32_e32 v144, s40, v137
	v_mfma_f32_16x16x32_bf16 v[90:93], v[236:239], v[204:207], v[90:93]
	v_mfma_f32_16x16x32_bf16 v[86:89], v[236:239], v[208:211], v[86:89]
	ds_read_b128 v[184:187], v144 offset:16384
	v_mfma_f32_16x16x32_bf16 v[82:85], v[236:239], v[212:215], v[82:85]
	ds_read_b128 v[188:191], v144 offset:17408
	v_mfma_f32_16x16x32_bf16 v[78:81], v[236:239], v[216:219], v[78:81]
	ds_read_b128 v[192:195], v144 offset:18432
	v_mfma_f32_16x16x32_bf16 v[74:77], v[236:239], v[220:223], v[74:77]
	ds_read_b128 v[196:199], v144 offset:19456
	s_add_i32 s42, s46, s41
	v_mfma_f32_16x16x32_bf16 v[70:73], v[236:239], v[224:227], v[70:73]
	s_mov_b32 m0, s42
	v_lshl_add_u64 v[142:143], v[132:133], 0, s[2:3]
	v_mfma_f32_16x16x32_bf16 v[66:69], v[236:239], v[228:231], v[66:69]
	global_load_lds_dwordx4 v[132:133], off
	s_addk_i32 m0, 0x1000
	v_mfma_f32_16x16x32_bf16 v[62:65], v[240:243], v[200:203], v[62:65]
;     ...
;   __syncthreads();
;   G2_STAGE(0); G2_STAGE(1);
;   const int fsw = (0x78 >> (((r16 >> 2) & 3) * 2)) & 3;
;   const int aoff = (wm * 128 + r16) * 64 + ((quad ^ fsw) << 4);
;   const int boff = 16384 + (wn * 64 + r16) * 64 + ((quad ^ fsw) << 4);
;   for (int kt = 0; kt < nk; kt++) {
;     if (kt + 1 < nk) asm volatile("s_waitcnt vmcnt(6)" ::: "memory");
;     else asm volatile("s_waitcnt vmcnt(0)" ::: "memory");
;     __builtin_amdgcn_s_barrier();
;     asm volatile("" ::: "memory");
;     if (kt + 2 < nk) G2_STAGE(kt + 2);
;     const char* cS = smem + (kt % 3) * 24576;
;     bf16x8 xa[8], wb[4];
; #pragma unroll
;     for (int f = 0; f < 8; f++) xa[f] = *(const bf16x8*)(cS + aoff + f * 1024);
; #pragma unroll
;     for (int f = 0; f < 4; f++) wb[f] = *(const bf16x8*)(cS + boff + f * 1024);
; #pragma unroll
;     for (int nf = 0; nf < 4; nf++)
; #pragma unroll
;       for (int mf = 0; mf < 8; mf++)
;         acc[nf][mf] = __builtin_amdgcn_mfma_f32_16x16x32_bf16(wb[nf], xa[mf], acc[nf][mf], 0, 0, 0);
;   }
	v_mfma_f32_16x16x32_bf16 v[58:61], v[240:243], v[204:207], v[58:61]
	v_mfma_f32_16x16x32_bf16 v[54:57], v[240:243], v[208:211], v[54:57]
	global_load_lds_dwordx4 v[142:143], off
	v_lshl_add_u64 v[142:143], v[142:143], 0, s[2:3]
	s_addk_i32 m0, 0x1000
	v_mfma_f32_16x16x32_bf16 v[50:53], v[240:243], v[212:215], v[50:53]
	v_mfma_f32_16x16x32_bf16 v[46:49], v[240:243], v[216:219], v[46:49]
	v_mfma_f32_16x16x32_bf16 v[42:45], v[240:243], v[220:223], v[42:45]
	global_load_lds_dwordx4 v[142:143], off
	v_lshl_add_u64 v[142:143], v[142:143], 0, s[2:3]
	s_addk_i32 m0, 0x1000
	v_mfma_f32_16x16x32_bf16 v[38:41], v[240:243], v[224:227], v[38:41]
	v_mfma_f32_16x16x32_bf16 v[34:37], v[240:243], v[228:231], v[34:37]
	v_mfma_f32_16x16x32_bf16 v[30:33], v[244:247], v[200:203], v[30:33]
	global_load_lds_dwordx4 v[142:143], off
	s_addk_i32 m0, 0x1000
	v_lshl_add_u64 v[142:143], v[134:135], 0, s[2:3]
	v_mfma_f32_16x16x32_bf16 v[26:29], v[244:247], v[204:207], v[26:29]
	v_mfma_f32_16x16x32_bf16 v[22:25], v[244:247], v[208:211], v[22:25]
	v_mfma_f32_16x16x32_bf16 v[18:21], v[244:247], v[212:215], v[18:21]
	global_load_lds_dwordx4 v[134:135], off
	s_addk_i32 m0, 0x1000
	v_lshl_add_u64 v[132:133], v[132:133], 0, s[12:13]
	v_mfma_f32_16x16x32_bf16 v[14:17], v[244:247], v[216:219], v[14:17]
	v_mfma_f32_16x16x32_bf16 v[10:13], v[244:247], v[220:223], v[10:13]
	v_mfma_f32_16x16x32_bf16 v[6:9], v[244:247], v[224:227], v[6:9]
	global_load_lds_dwordx4 v[142:143], off
	v_lshl_add_u64 v[134:135], v[134:135], 0, s[4:5]
	v_mfma_f32_16x16x32_bf16 v[2:5], v[244:247], v[228:231], v[2:5]
	s_mov_b32 s41, s40
	s_add_i32 s40, s40, 0x6000
	s_cmp_eq_u32 s40, 0x12000
	s_cselect_b32 s40, 0, s40
	s_sub_i32 s39, s39, 1
	s_cmp_lg_u32 s39, 0
	s_cbranch_scc1 .Lt8_loop
	s_waitcnt vmcnt(6) lgkmcnt(0)
	s_barrier
	v_add_u32_e32 v144, s40, v136
	v_mfma_f32_16x16x32_bf16 v[126:129], v[184:187], v[146:149], v[126:129]
	ds_read_b128 v[200:203], v144 offset:0
	v_mfma_f32_16x16x32_bf16 v[122:125], v[184:187], v[152:155], v[122:125]
	ds_read_b128 v[204:207], v144 offset:1024
	v_mfma_f32_16x16x32_bf16 v[118:121], v[184:187], v[156:159], v[118:121]
	ds_read_b128 v[208:211], v144 offset:2048
	v_mfma_f32_16x16x32_bf16 v[114:117], v[184:187], v[162:165], v[114:117]
	ds_read_b128 v[212:215], v144 offset:3072
	v_mfma_f32_16x16x32_bf16 v[110:113], v[184:187], v[166:169], v[110:113]
	ds_read_b128 v[216:219], v144 offset:4096
	v_mfma_f32_16x16x32_bf16 v[106:109], v[184:187], v[170:173], v[106:109]
	ds_read_b128 v[220:223], v144 offset:5120
	v_mfma_f32_16x16x32_bf16 v[102:105], v[184:187], v[176:179], v[102:105]
	ds_read_b128 v[224:227], v144 offset:6144
	v_mfma_f32_16x16x32_bf16 v[98:101], v[184:187], v[180:183], v[98:101]
	ds_read_b128 v[228:231], v144 offset:7168
	v_mfma_f32_16x16x32_bf16 v[94:97], v[188:191], v[146:149], v[94:97]
	v_add_u32_e32 v144, s40, v137
	v_mfma_f32_16x16x32_bf16 v[90:93], v[188:191], v[152:155], v[90:93]
	v_mfma_f32_16x16x32_bf16 v[86:89], v[188:191], v[156:159], v[86:89]
	ds_read_b128 v[232:235], v144 offset:16384
	v_mfma_f32_16x16x32_bf16 v[82:85], v[188:191], v[162:165], v[82:85]
	ds_read_b128 v[236:239], v144 offset:17408
	v_mfma_f32_16x16x32_bf16 v[78:81], v[188:191], v[166:169], v[78:81]
	ds_read_b128 v[240:243], v144 offset:18432
	v_mfma_f32_16x16x32_bf16 v[74:77], v[188:191], v[170:173], v[74:77]
	ds_read_b128 v[244:247], v144 offset:19456
	s_add_i32 s42, s46, s41
	v_mfma_f32_16x16x32_bf16 v[70:73], v[188:191], v[176:179], v[70:73]
	s_mov_b32 m0, s42
	v_lshl_add_u64 v[142:143], v[132:133], 0, s[2:3]
	v_mfma_f32_16x16x32_bf16 v[66:69], v[188:191], v[180:183], v[66:69]
	global_load_lds_dwordx4 v[132:133], off
	s_addk_i32 m0, 0x1000
	v_mfma_f32_16x16x32_bf16 v[62:65], v[192:195], v[146:149], v[62:65]
	v_mfma_f32_16x16x32_bf16 v[58:61], v[192:195], v[152:155], v[58:61]
	v_mfma_f32_16x16x32_bf16 v[54:57], v[192:195], v[156:159], v[54:57]
	global_load_lds_dwordx4 v[142:143], off
	v_lshl_add_u64 v[142:143], v[142:143], 0, s[2:3]
	s_addk_i32 m0, 0x1000
	v_mfma_f32_16x16x32_bf16 v[50:53], v[192:195], v[162:165], v[50:53]
	v_mfma_f32_16x16x32_bf16 v[46:49], v[192:195], v[166:169], v[46:49]
	v_mfma_f32_16x16x32_bf16 v[42:45], v[192:195], v[170:173], v[42:45]
	global_load_lds_dwordx4 v[142:143], off
	v_lshl_add_u64 v[142:143], v[142:143], 0, s[2:3]
	s_addk_i32 m0, 0x1000
	v_mfma_f32_16x16x32_bf16 v[38:41], v[192:195], v[176:179], v[38:41]
	v_mfma_f32_16x16x32_bf16 v[34:37], v[192:195], v[180:183], v[34:37]
	v_mfma_f32_16x16x32_bf16 v[30:33], v[196:199], v[146:149], v[30:33]
	global_load_lds_dwordx4 v[142:143], off
	s_addk_i32 m0, 0x1000
	v_lshl_add_u64 v[142:143], v[134:135], 0, s[2:3]
	v_mfma_f32_16x16x32_bf16 v[26:29], v[196:199], v[152:155], v[26:29]
	v_mfma_f32_16x16x32_bf16 v[22:25], v[196:199], v[156:159], v[22:25]
	v_mfma_f32_16x16x32_bf16 v[18:21], v[196:199], v[162:165], v[18:21]
	global_load_lds_dwordx4 v[134:135], off
	s_addk_i32 m0, 0x1000
	v_lshl_add_u64 v[132:133], v[132:133], 0, s[12:13]
	v_mfma_f32_16x16x32_bf16 v[14:17], v[196:199], v[166:169], v[14:17]
	v_mfma_f32_16x16x32_bf16 v[10:13], v[196:199], v[170:173], v[10:13]
	v_mfma_f32_16x16x32_bf16 v[6:9], v[196:199], v[176:179], v[6:9]
	global_load_lds_dwordx4 v[142:143], off
	v_lshl_add_u64 v[134:135], v[134:135], 0, s[4:5]
	v_mfma_f32_16x16x32_bf16 v[2:5], v[196:199], v[180:183], v[2:5]
	s_mov_b32 s41, s40
	s_add_i32 s40, s40, 0x6000
	s_cmp_eq_u32 s40, 0x12000
	s_cselect_b32 s40, 0, s40
	s_waitcnt vmcnt(6) lgkmcnt(0)
	s_barrier
;     ...
;   for (int kt = 0; kt < nk; kt++) {
;     if (kt + 1 < nk) asm volatile("s_waitcnt vmcnt(6)" ::: "memory");
;     else asm volatile("s_waitcnt vmcnt(0)" ::: "memory");
;     __builtin_amdgcn_s_barrier();
;     asm volatile("" ::: "memory");
;     if (kt + 2 < nk) G2_STAGE(kt + 2);
;     const char* cS = smem + (kt % 3) * 24576;
;     bf16x8 xa[8], wb[4];
; #pragma unroll
;     for (int f = 0; f < 8; f++) xa[f] = *(const bf16x8*)(cS + aoff + f * 1024);
; #pragma unroll
;     for (int f = 0; f < 4; f++) wb[f] = *(const bf16x8*)(cS + boff + f * 1024);
; #pragma unroll
;     for (int nf = 0; nf < 4; nf++)
; #pragma unroll
;       for (int mf = 0; mf < 8; mf++)
;         acc[nf][mf] = __builtin_amdgcn_mfma_f32_16x16x32_bf16(wb[nf], xa[mf], acc[nf][mf], 0, 0, 0);
;   }
	v_add_u32_e32 v144, s40, v136
	v_mfma_f32_16x16x32_bf16 v[126:129], v[232:235], v[200:203], v[126:129]
	ds_read_b128 v[146:149], v144 offset:0
	v_mfma_f32_16x16x32_bf16 v[122:125], v[232:235], v[204:207], v[122:125]
	ds_read_b128 v[152:155], v144 offset:1024
	v_mfma_f32_16x16x32_bf16 v[118:121], v[232:235], v[208:211], v[118:121]
	ds_read_b128 v[156:159], v144 offset:2048
	v_mfma_f32_16x16x32_bf16 v[114:117], v[232:235], v[212:215], v[114:117]
	ds_read_b128 v[162:165], v144 offset:3072
	v_mfma_f32_16x16x32_bf16 v[110:113], v[232:235], v[216:219], v[110:113]
	ds_read_b128 v[166:169], v144 offset:4096
	v_mfma_f32_16x16x32_bf16 v[106:109], v[232:235], v[220:223], v[106:109]
	ds_read_b128 v[170:173], v144 offset:5120
	v_mfma_f32_16x16x32_bf16 v[102:105], v[232:235], v[224:227], v[102:105]
	ds_read_b128 v[176:179], v144 offset:6144
	v_mfma_f32_16x16x32_bf16 v[98:101], v[232:235], v[228:231], v[98:101]
	ds_read_b128 v[180:183], v144 offset:7168
	v_mfma_f32_16x16x32_bf16 v[94:97], v[236:239], v[200:203], v[94:97]
	v_add_u32_e32 v144, s40, v137
	v_mfma_f32_16x16x32_bf16 v[90:93], v[236:239], v[204:207], v[90:93]
	v_mfma_f32_16x16x32_bf16 v[86:89], v[236:239], v[208:211], v[86:89]
	ds_read_b128 v[184:187], v144 offset:16384
	v_mfma_f32_16x16x32_bf16 v[82:85], v[236:239], v[212:215], v[82:85]
	ds_read_b128 v[188:191], v144 offset:17408
	v_mfma_f32_16x16x32_bf16 v[78:81], v[236:239], v[216:219], v[78:81]
	ds_read_b128 v[192:195], v144 offset:18432
	v_mfma_f32_16x16x32_bf16 v[74:77], v[236:239], v[220:223], v[74:77]
	ds_read_b128 v[196:199], v144 offset:19456
	v_mfma_f32_16x16x32_bf16 v[70:73], v[236:239], v[224:227], v[70:73]
	v_mfma_f32_16x16x32_bf16 v[66:69], v[236:239], v[228:231], v[66:69]
	v_mfma_f32_16x16x32_bf16 v[62:65], v[240:243], v[200:203], v[62:65]
	v_mfma_f32_16x16x32_bf16 v[58:61], v[240:243], v[204:207], v[58:61]
	v_mfma_f32_16x16x32_bf16 v[54:57], v[240:243], v[208:211], v[54:57]
	v_mfma_f32_16x16x32_bf16 v[50:53], v[240:243], v[212:215], v[50:53]
	v_mfma_f32_16x16x32_bf16 v[46:49], v[240:243], v[216:219], v[46:49]
	v_mfma_f32_16x16x32_bf16 v[42:45], v[240:243], v[220:223], v[42:45]
	v_mfma_f32_16x16x32_bf16 v[38:41], v[240:243], v[224:227], v[38:41]
	v_mfma_f32_16x16x32_bf16 v[34:37], v[240:243], v[228:231], v[34:37]
	v_mfma_f32_16x16x32_bf16 v[30:33], v[244:247], v[200:203], v[30:33]
	v_mfma_f32_16x16x32_bf16 v[26:29], v[244:247], v[204:207], v[26:29]
	v_mfma_f32_16x16x32_bf16 v[22:25], v[244:247], v[208:211], v[22:25]
	v_mfma_f32_16x16x32_bf16 v[18:21], v[244:247], v[212:215], v[18:21]
	v_mfma_f32_16x16x32_bf16 v[14:17], v[244:247], v[216:219], v[14:17]
	v_mfma_f32_16x16x32_bf16 v[10:13], v[244:247], v[220:223], v[10:13]
	v_mfma_f32_16x16x32_bf16 v[6:9], v[244:247], v[224:227], v[6:9]
	v_mfma_f32_16x16x32_bf16 v[2:5], v[244:247], v[228:231], v[2:5]
	s_mov_b32 s41, s40
	s_add_i32 s40, s40, 0x6000
	s_cmp_eq_u32 s40, 0x12000
	s_cselect_b32 s40, 0, s40
	s_waitcnt vmcnt(0) lgkmcnt(0)
	s_barrier
	v_add_u32_e32 v144, s40, v136
	v_mfma_f32_16x16x32_bf16 v[126:129], v[184:187], v[146:149], v[126:129]
	ds_read_b128 v[200:203], v144 offset:0
	v_mfma_f32_16x16x32_bf16 v[122:125], v[184:187], v[152:155], v[122:125]
	ds_read_b128 v[204:207], v144 offset:1024
	v_mfma_f32_16x16x32_bf16 v[118:121], v[184:187], v[156:159], v[118:121]
	ds_read_b128 v[208:211], v144 offset:2048
	v_mfma_f32_16x16x32_bf16 v[114:117], v[184:187], v[162:165], v[114:117]
	ds_read_b128 v[212:215], v144 offset:3072
	v_mfma_f32_16x16x32_bf16 v[110:113], v[184:187], v[166:169], v[110:113]
	ds_read_b128 v[216:219], v144 offset:4096
	v_mfma_f32_16x16x32_bf16 v[106:109], v[184:187], v[170:173], v[106:109]
	ds_read_b128 v[220:223], v144 offset:5120
	v_mfma_f32_16x16x32_bf16 v[102:105], v[184:187], v[176:179], v[102:105]
	ds_read_b128 v[224:227], v144 offset:6144
	v_mfma_f32_16x16x32_bf16 v[98:101], v[184:187], v[180:183], v[98:101]
	ds_read_b128 v[228:231], v144 offset:7168
	v_mfma_f32_16x16x32_bf16 v[94:97], v[188:191], v[146:149], v[94:97]
	v_add_u32_e32 v144, s40, v137
	v_mfma_f32_16x16x32_bf16 v[90:93], v[188:191], v[152:155], v[90:93]
	v_mfma_f32_16x16x32_bf16 v[86:89], v[188:191], v[156:159], v[86:89]
	ds_read_b128 v[232:235], v144 offset:16384
	v_mfma_f32_16x16x32_bf16 v[82:85], v[188:191], v[162:165], v[82:85]
	ds_read_b128 v[236:239], v144 offset:17408
	v_mfma_f32_16x16x32_bf16 v[78:81], v[188:191], v[166:169], v[78:81]
	ds_read_b128 v[240:243], v144 offset:18432
	v_mfma_f32_16x16x32_bf16 v[74:77], v[188:191], v[170:173], v[74:77]
	ds_read_b128 v[244:247], v144 offset:19456
	v_mfma_f32_16x16x32_bf16 v[70:73], v[188:191], v[176:179], v[70:73]
	v_mfma_f32_16x16x32_bf16 v[66:69], v[188:191], v[180:183], v[66:69]
	v_mfma_f32_16x16x32_bf16 v[62:65], v[192:195], v[146:149], v[62:65]
	v_mfma_f32_16x16x32_bf16 v[58:61], v[192:195], v[152:155], v[58:61]
	v_mfma_f32_16x16x32_bf16 v[54:57], v[192:195], v[156:159], v[54:57]
	v_mfma_f32_16x16x32_bf16 v[50:53], v[192:195], v[162:165], v[50:53]
	v_mfma_f32_16x16x32_bf16 v[46:49], v[192:195], v[166:169], v[46:49]
	v_mfma_f32_16x16x32_bf16 v[42:45], v[192:195], v[170:173], v[42:45]
	v_mfma_f32_16x16x32_bf16 v[38:41], v[192:195], v[176:179], v[38:41]
	v_mfma_f32_16x16x32_bf16 v[34:37], v[192:195], v[180:183], v[34:37]
	v_mfma_f32_16x16x32_bf16 v[30:33], v[196:199], v[146:149], v[30:33]
	v_mfma_f32_16x16x32_bf16 v[26:29], v[196:199], v[152:155], v[26:29]
	v_mfma_f32_16x16x32_bf16 v[22:25], v[196:199], v[156:159], v[22:25]
	v_mfma_f32_16x16x32_bf16 v[18:21], v[196:199], v[162:165], v[18:21]
	v_mfma_f32_16x16x32_bf16 v[14:17], v[196:199], v[166:169], v[14:17]
	v_mfma_f32_16x16x32_bf16 v[10:13], v[196:199], v[170:173], v[10:13]
	v_mfma_f32_16x16x32_bf16 v[6:9], v[196:199], v[176:179], v[6:9]
	v_mfma_f32_16x16x32_bf16 v[2:5], v[196:199], v[180:183], v[2:5]
	s_mov_b32 s41, s40
	s_add_i32 s40, s40, 0x6000
	s_cmp_eq_u32 s40, 0x12000
	s_cselect_b32 s40, 0, s40
	s_mov_b32 s4, 0x8000
	s_mov_b32 s5, 0
	s_mov_b32 s10, 0x10000
	s_mov_b32 s11, 0
	s_mov_b32 s44, 0x3fd744fd
	s_waitcnt lgkmcnt(0)
; DEVI float blo(unsigned u) { return __uint_as_float(u << 16); }
; DEVI float bhi(unsigned u) { return __uint_as_float(u & 0xffff0000u); }
;     ...
;   for (int kt = 0; kt < nk; kt++) {
;     if (kt + 1 < nk) asm volatile("s_waitcnt vmcnt(6)" ::: "memory");
;     else asm volatile("s_waitcnt vmcnt(0)" ::: "memory");
;     __builtin_amdgcn_s_barrier();
;     asm volatile("" ::: "memory");
;     if (kt + 2 < nk) G2_STAGE(kt + 2);
;     const char* cS = smem + (kt % 3) * 24576;
;     bf16x8 xa[8], wb[4];
; #pragma unroll
;     for (int f = 0; f < 8; f++) xa[f] = *(const bf16x8*)(cS + aoff + f * 1024);
; #pragma unroll
;     for (int f = 0; f < 4; f++) wb[f] = *(const bf16x8*)(cS + boff + f * 1024);
; #pragma unroll
;     for (int nf = 0; nf < 4; nf++)
; #pragma unroll
;       for (int mf = 0; mf < 8; mf++)
;         acc[nf][mf] = __builtin_amdgcn_mfma_f32_16x16x32_bf16(wb[nf], xa[mf], acc[nf][mf], 0, 0, 0);
;   }
;     ...
; #pragma unroll
;       for (int nf = 0; nf < 4; nf++) {
;         const int col = n0 + wn * 64 + nf * 16 + quad * 4;
;         f32x4 a = acc[nf][mf];
;         if (EPI == EPI_RESID || EPI == EPI_RESID_ATOMIC) {
;           f32x4 x = a;
;           if (EPI == EPI_RESID || kpart == 0) {
;             const u32x2 xr = *(const u32x2*)((const u16*)(p.ws + WS_XB) + (size_t)row * 1024 + col);
;             x[0] += ALPHA * blo(xr[0]); x[1] += ALPHA * bhi(xr[0]); x[2] += ALPHA * blo(xr[1]); x[3] += ALPHA * bhi(xr[1]);
;           }
;           if (EPI == EPI_RESID) *(f32x4*)((float*)(p.ws + WS_XF) + (size_t)row * 1024 + col) = x;
;           else *(f32x4*)((float*)(p.ws + WS_SLAB) + ((size_t)kpart * 512 + (row - T_P)) * 1024 + col) = x;
	v_mfma_f32_16x16x32_bf16 v[126:129], v[232:235], v[200:203], v[126:129]
	v_mfma_f32_16x16x32_bf16 v[122:125], v[232:235], v[204:207], v[122:125]
	v_mfma_f32_16x16x32_bf16 v[118:121], v[232:235], v[208:211], v[118:121]
	v_mfma_f32_16x16x32_bf16 v[114:117], v[232:235], v[212:215], v[114:117]
	v_mfma_f32_16x16x32_bf16 v[110:113], v[232:235], v[216:219], v[110:113]
	global_load_dwordx4 v[146:149], v[138:139], off offset:0
	v_mfma_f32_16x16x32_bf16 v[106:109], v[232:235], v[220:223], v[106:109]
	v_mfma_f32_16x16x32_bf16 v[102:105], v[232:235], v[224:227], v[102:105]
	global_load_dwordx4 v[152:155], v[138:139], off offset:64
	v_mfma_f32_16x16x32_bf16 v[98:101], v[232:235], v[228:231], v[98:101]
	v_lshl_add_u64 v[138:139], v[138:139], 0, s[4:5]
	v_mfma_f32_16x16x32_bf16 v[94:97], v[236:239], v[200:203], v[94:97]
	global_load_dwordx4 v[156:159], v[138:139], off offset:0
	v_mfma_f32_16x16x32_bf16 v[90:93], v[236:239], v[204:207], v[90:93]
	v_mfma_f32_16x16x32_bf16 v[86:89], v[236:239], v[208:211], v[86:89]
	global_load_dwordx4 v[162:165], v[138:139], off offset:64
	v_mfma_f32_16x16x32_bf16 v[82:85], v[236:239], v[212:215], v[82:85]
	v_lshl_add_u64 v[138:139], v[138:139], 0, s[4:5]
	v_mfma_f32_16x16x32_bf16 v[78:81], v[236:239], v[216:219], v[78:81]
	global_load_dwordx4 v[166:169], v[138:139], off offset:0
	v_mfma_f32_16x16x32_bf16 v[74:77], v[236:239], v[220:223], v[74:77]
	v_mfma_f32_16x16x32_bf16 v[70:73], v[236:239], v[224:227], v[70:73]
	global_load_dwordx4 v[170:173], v[138:139], off offset:64
	v_mfma_f32_16x16x32_bf16 v[66:69], v[236:239], v[228:231], v[66:69]
	v_lshl_add_u64 v[138:139], v[138:139], 0, s[4:5]
	v_mfma_f32_16x16x32_bf16 v[62:65], v[240:243], v[200:203], v[62:65]
	global_load_dwordx4 v[176:179], v[138:139], off offset:0
	v_mfma_f32_16x16x32_bf16 v[58:61], v[240:243], v[204:207], v[58:61]
	v_mfma_f32_16x16x32_bf16 v[54:57], v[240:243], v[208:211], v[54:57]
	global_load_dwordx4 v[180:183], v[138:139], off offset:64
	v_mfma_f32_16x16x32_bf16 v[50:53], v[240:243], v[212:215], v[50:53]
	v_lshl_add_u64 v[138:139], v[138:139], 0, s[4:5]
	v_mfma_f32_16x16x32_bf16 v[46:49], v[240:243], v[216:219], v[46:49]
	global_load_dwordx4 v[184:187], v[138:139], off offset:0
	v_mfma_f32_16x16x32_bf16 v[42:45], v[240:243], v[220:223], v[42:45]
	v_mfma_f32_16x16x32_bf16 v[38:41], v[240:243], v[224:227], v[38:41]
	global_load_dwordx4 v[188:191], v[138:139], off offset:64
	v_mfma_f32_16x16x32_bf16 v[34:37], v[240:243], v[228:231], v[34:37]
	v_lshl_add_u64 v[138:139], v[138:139], 0, s[4:5]
	v_mfma_f32_16x16x32_bf16 v[30:33], v[244:247], v[200:203], v[30:33]
	global_load_dwordx4 v[192:195], v[138:139], off offset:0
	v_mfma_f32_16x16x32_bf16 v[26:29], v[244:247], v[204:207], v[26:29]
	v_mfma_f32_16x16x32_bf16 v[22:25], v[244:247], v[208:211], v[22:25]
	global_load_dwordx4 v[196:199], v[138:139], off offset:64
	v_mfma_f32_16x16x32_bf16 v[18:21], v[244:247], v[212:215], v[18:21]
	v_lshl_add_u64 v[138:139], v[138:139], 0, s[4:5]
	v_mfma_f32_16x16x32_bf16 v[14:17], v[244:247], v[216:219], v[14:17]
	v_mfma_f32_16x16x32_bf16 v[10:13], v[244:247], v[220:223], v[10:13]
	v_mfma_f32_16x16x32_bf16 v[6:9], v[244:247], v[224:227], v[6:9]
	v_mfma_f32_16x16x32_bf16 v[2:5], v[244:247], v[228:231], v[2:5]
	s_mov_b32 m0, s43
	global_load_dwordx4 v[200:203], v[138:139], off offset:0
	global_load_dwordx4 v[204:207], v[138:139], off offset:64
	v_lshl_add_u64 v[138:139], v[138:139], 0, s[4:5]
	global_load_dwordx4 v[208:211], v[138:139], off offset:0
	global_load_dwordx4 v[212:215], v[138:139], off offset:64
	v_lshl_add_u64 v[138:139], v[138:139], 0, s[4:5]
	s_nop 7
	s_waitcnt vmcnt(15)
	v_permlane16_swap_b32_e32 v146, v148
	v_permlane16_swap_b32_e32 v147, v149
	v_lshlrev_b32_e32 v216, 16, v146
	v_and_b32_e32 v146, 0xffff0000, v146
	v_lshlrev_b32_e32 v217, 16, v147
	v_and_b32_e32 v147, 0xffff0000, v147
	v_fmac_f32_e32 v126, s44, v216
	v_fmac_f32_e32 v127, s44, v146
	v_fmac_f32_e32 v128, s44, v217
	v_fmac_f32_e32 v129, s44, v147
	global_store_dwordx4 v[140:141], v[126:129], off offset:0
	v_lshlrev_b32_e32 v216, 16, v148
	v_and_b32_e32 v148, 0xffff0000, v148
	v_lshlrev_b32_e32 v217, 16, v149
	v_and_b32_e32 v149, 0xffff0000, v149
	v_fmac_f32_e32 v94, s44, v216
	v_fmac_f32_e32 v95, s44, v148
	v_fmac_f32_e32 v96, s44, v217
	v_fmac_f32_e32 v97, s44, v149
	global_store_dwordx4 v[140:141], v[94:97], off offset:64
	s_waitcnt vmcnt(16)
	v_permlane16_swap_b32_e32 v152, v154
	v_permlane16_swap_b32_e32 v153, v155
	v_lshlrev_b32_e32 v216, 16, v152
	v_and_b32_e32 v152, 0xffff0000, v152
	v_lshlrev_b32_e32 v217, 16, v153
	v_and_b32_e32 v153, 0xffff0000, v153
	v_fmac_f32_e32 v62, s44, v216
	v_fmac_f32_e32 v63, s44, v152
	v_fmac_f32_e32 v64, s44, v217
	v_fmac_f32_e32 v65, s44, v153
	global_store_dwordx4 v[140:141], v[62:65], off offset:128
	v_lshlrev_b32_e32 v216, 16, v154
	v_and_b32_e32 v154, 0xffff0000, v154
	v_lshlrev_b32_e32 v217, 16, v155
	v_and_b32_e32 v155, 0xffff0000, v155
	v_fmac_f32_e32 v30, s44, v216
	v_fmac_f32_e32 v31, s44, v154
	v_fmac_f32_e32 v32, s44, v217
	v_fmac_f32_e32 v33, s44, v155
	global_store_dwordx4 v[140:141], v[30:33], off offset:192
	v_lshl_add_u64 v[140:141], v[140:141], 0, s[10:11]
	s_waitcnt vmcnt(17)
	v_permlane16_swap_b32_e32 v156, v158
	v_permlane16_swap_b32_e32 v157, v159
	v_lshlrev_b32_e32 v216, 16, v156
	v_and_b32_e32 v156, 0xffff0000, v156
	v_lshlrev_b32_e32 v217, 16, v157
	v_and_b32_e32 v157, 0xffff0000, v157
	v_fmac_f32_e32 v122, s44, v216
	v_fmac_f32_e32 v123, s44, v156
	v_fmac_f32_e32 v124, s44, v217
	v_fmac_f32_e32 v125, s44, v157
	global_store_dwordx4 v[140:141], v[122:125], off offset:0
	v_lshlrev_b32_e32 v216, 16, v158
	v_and_b32_e32 v158, 0xffff0000, v158
	v_lshlrev_b32_e32 v217, 16, v159
	v_and_b32_e32 v159, 0xffff0000, v159
	v_fmac_f32_e32 v90, s44, v216
	v_fmac_f32_e32 v91, s44, v158
	v_fmac_f32_e32 v92, s44, v217
	v_fmac_f32_e32 v93, s44, v159
	global_store_dwordx4 v[140:141], v[90:93], off offset:64
	s_waitcnt vmcnt(18)
; DEVI float blo(unsigned u) { return __uint_as_float(u << 16); }
; DEVI float bhi(unsigned u) { return __uint_as_float(u & 0xffff0000u); }
;     ...
; #pragma unroll
;       for (int nf = 0; nf < 4; nf++) {
;         const int col = n0 + wn * 64 + nf * 16 + quad * 4;
;         f32x4 a = acc[nf][mf];
;         if (EPI == EPI_RESID || EPI == EPI_RESID_ATOMIC) {
;           f32x4 x = a;
;           if (EPI == EPI_RESID || kpart == 0) {
;             const u32x2 xr = *(const u32x2*)((const u16*)(p.ws + WS_XB) + (size_t)row * 1024 + col);
;             x[0] += ALPHA * blo(xr[0]); x[1] += ALPHA * bhi(xr[0]); x[2] += ALPHA * blo(xr[1]); x[3] += ALPHA * bhi(xr[1]);
;           }
;           if (EPI == EPI_RESID) *(f32x4*)((float*)(p.ws + WS_XF) + (size_t)row * 1024 + col) = x;
;           else *(f32x4*)((float*)(p.ws + WS_SLAB) + ((size_t)kpart * 512 + (row - T_P)) * 1024 + col) = x;
	v_permlane16_swap_b32_e32 v162, v164
	v_permlane16_swap_b32_e32 v163, v165
	v_lshlrev_b32_e32 v216, 16, v162
	v_and_b32_e32 v162, 0xffff0000, v162
	v_lshlrev_b32_e32 v217, 16, v163
	v_and_b32_e32 v163, 0xffff0000, v163
	v_fmac_f32_e32 v58, s44, v216
	v_fmac_f32_e32 v59, s44, v162
	v_fmac_f32_e32 v60, s44, v217
	v_fmac_f32_e32 v61, s44, v163
	global_store_dwordx4 v[140:141], v[58:61], off offset:128
	v_lshlrev_b32_e32 v216, 16, v164
	v_and_b32_e32 v164, 0xffff0000, v164
	v_lshlrev_b32_e32 v217, 16, v165
	v_and_b32_e32 v165, 0xffff0000, v165
	v_fmac_f32_e32 v26, s44, v216
	v_fmac_f32_e32 v27, s44, v164
	v_fmac_f32_e32 v28, s44, v217
	v_fmac_f32_e32 v29, s44, v165
	global_store_dwordx4 v[140:141], v[26:29], off offset:192
	v_lshl_add_u64 v[140:141], v[140:141], 0, s[10:11]
	s_waitcnt vmcnt(19)
	v_permlane16_swap_b32_e32 v166, v168
	v_permlane16_swap_b32_e32 v167, v169
	v_lshlrev_b32_e32 v216, 16, v166
	v_and_b32_e32 v166, 0xffff0000, v166
	v_lshlrev_b32_e32 v217, 16, v167
	v_and_b32_e32 v167, 0xffff0000, v167
	v_fmac_f32_e32 v118, s44, v216
	v_fmac_f32_e32 v119, s44, v166
	v_fmac_f32_e32 v120, s44, v217
	v_fmac_f32_e32 v121, s44, v167
	global_store_dwordx4 v[140:141], v[118:121], off offset:0
	v_lshlrev_b32_e32 v216, 16, v168
	v_and_b32_e32 v168, 0xffff0000, v168
	v_lshlrev_b32_e32 v217, 16, v169
	v_and_b32_e32 v169, 0xffff0000, v169
	v_fmac_f32_e32 v86, s44, v216
	v_fmac_f32_e32 v87, s44, v168
	v_fmac_f32_e32 v88, s44, v217
	v_fmac_f32_e32 v89, s44, v169
	global_store_dwordx4 v[140:141], v[86:89], off offset:64
	s_waitcnt vmcnt(20)
	v_permlane16_swap_b32_e32 v170, v172
	v_permlane16_swap_b32_e32 v171, v173
	v_lshlrev_b32_e32 v216, 16, v170
	v_and_b32_e32 v170, 0xffff0000, v170
	v_lshlrev_b32_e32 v217, 16, v171
	v_and_b32_e32 v171, 0xffff0000, v171
	v_fmac_f32_e32 v54, s44, v216
	v_fmac_f32_e32 v55, s44, v170
	v_fmac_f32_e32 v56, s44, v217
	v_fmac_f32_e32 v57, s44, v171
	global_store_dwordx4 v[140:141], v[54:57], off offset:128
	v_lshlrev_b32_e32 v216, 16, v172
	v_and_b32_e32 v172, 0xffff0000, v172
	v_lshlrev_b32_e32 v217, 16, v173
	v_and_b32_e32 v173, 0xffff0000, v173
	v_fmac_f32_e32 v22, s44, v216
	v_fmac_f32_e32 v23, s44, v172
	v_fmac_f32_e32 v24, s44, v217
	v_fmac_f32_e32 v25, s44, v173
	global_store_dwordx4 v[140:141], v[22:25], off offset:192
	v_lshl_add_u64 v[140:141], v[140:141], 0, s[10:11]
	s_waitcnt vmcnt(21)
	v_permlane16_swap_b32_e32 v176, v178
	v_permlane16_swap_b32_e32 v177, v179
	v_lshlrev_b32_e32 v216, 16, v176
	v_and_b32_e32 v176, 0xffff0000, v176
	v_lshlrev_b32_e32 v217, 16, v177
	v_and_b32_e32 v177, 0xffff0000, v177
	v_fmac_f32_e32 v114, s44, v216
	v_fmac_f32_e32 v115, s44, v176
	v_fmac_f32_e32 v116, s44, v217
	v_fmac_f32_e32 v117, s44, v177
	global_store_dwordx4 v[140:141], v[114:117], off offset:0
	v_lshlrev_b32_e32 v216, 16, v178
	v_and_b32_e32 v178, 0xffff0000, v178
	v_lshlrev_b32_e32 v217, 16, v179
	v_and_b32_e32 v179, 0xffff0000, v179
	v_fmac_f32_e32 v82, s44, v216
	v_fmac_f32_e32 v83, s44, v178
	v_fmac_f32_e32 v84, s44, v217
	v_fmac_f32_e32 v85, s44, v179
	global_store_dwordx4 v[140:141], v[82:85], off offset:64
	s_waitcnt vmcnt(22)
	v_permlane16_swap_b32_e32 v180, v182
	v_permlane16_swap_b32_e32 v181, v183
	v_lshlrev_b32_e32 v216, 16, v180
	v_and_b32_e32 v180, 0xffff0000, v180
	v_lshlrev_b32_e32 v217, 16, v181
	v_and_b32_e32 v181, 0xffff0000, v181
	v_fmac_f32_e32 v50, s44, v216
	v_fmac_f32_e32 v51, s44, v180
	v_fmac_f32_e32 v52, s44, v217
	v_fmac_f32_e32 v53, s44, v181
	global_store_dwordx4 v[140:141], v[50:53], off offset:128
	v_lshlrev_b32_e32 v216, 16, v182
	v_and_b32_e32 v182, 0xffff0000, v182
	v_lshlrev_b32_e32 v217, 16, v183
	v_and_b32_e32 v183, 0xffff0000, v183
	v_fmac_f32_e32 v18, s44, v216
	v_fmac_f32_e32 v19, s44, v182
	v_fmac_f32_e32 v20, s44, v217
	v_fmac_f32_e32 v21, s44, v183
	global_store_dwordx4 v[140:141], v[18:21], off offset:192
	v_lshl_add_u64 v[140:141], v[140:141], 0, s[10:11]
	s_waitcnt vmcnt(23)
	v_permlane16_swap_b32_e32 v184, v186
	v_permlane16_swap_b32_e32 v185, v187
	v_lshlrev_b32_e32 v216, 16, v184
	v_and_b32_e32 v184, 0xffff0000, v184
	v_lshlrev_b32_e32 v217, 16, v185
	v_and_b32_e32 v185, 0xffff0000, v185
	v_fmac_f32_e32 v110, s44, v216
	v_fmac_f32_e32 v111, s44, v184
	v_fmac_f32_e32 v112, s44, v217
	v_fmac_f32_e32 v113, s44, v185
	global_store_dwordx4 v[140:141], v[110:113], off offset:0
	v_lshlrev_b32_e32 v216, 16, v186
	v_and_b32_e32 v186, 0xffff0000, v186
	v_lshlrev_b32_e32 v217, 16, v187
	v_and_b32_e32 v187, 0xffff0000, v187
	v_fmac_f32_e32 v78, s44, v216
	v_fmac_f32_e32 v79, s44, v186
	v_fmac_f32_e32 v80, s44, v217
	v_fmac_f32_e32 v81, s44, v187
	global_store_dwordx4 v[140:141], v[78:81], off offset:64
	s_waitcnt vmcnt(24)
	v_permlane16_swap_b32_e32 v188, v190
	v_permlane16_swap_b32_e32 v189, v191
	v_lshlrev_b32_e32 v216, 16, v188
	v_and_b32_e32 v188, 0xffff0000, v188
	v_lshlrev_b32_e32 v217, 16, v189
	v_and_b32_e32 v189, 0xffff0000, v189
	v_fmac_f32_e32 v46, s44, v216
	v_fmac_f32_e32 v47, s44, v188
	v_fmac_f32_e32 v48, s44, v217
	v_fmac_f32_e32 v49, s44, v189
	global_store_dwordx4 v[140:141], v[46:49], off offset:128
	v_lshlrev_b32_e32 v216, 16, v190
	v_and_b32_e32 v190, 0xffff0000, v190
	v_lshlrev_b32_e32 v217, 16, v191
	v_and_b32_e32 v191, 0xffff0000, v191
	v_fmac_f32_e32 v14, s44, v216
	v_fmac_f32_e32 v15, s44, v190
	v_fmac_f32_e32 v16, s44, v217
	v_fmac_f32_e32 v17, s44, v191
	global_store_dwordx4 v[140:141], v[14:17], off offset:192
	v_lshl_add_u64 v[140:141], v[140:141], 0, s[10:11]
	s_waitcnt vmcnt(25)
; DEVI float blo(unsigned u) { return __uint_as_float(u << 16); }
; DEVI float bhi(unsigned u) { return __uint_as_float(u & 0xffff0000u); }
; DEVI int xcd_first_tile() { return (blockIdx.x & 7) * (gridDim.x >> 3) + (blockIdx.x >> 3); }
;     ...
; #pragma unroll
;       for (int nf = 0; nf < 4; nf++) {
;         const int col = n0 + wn * 64 + nf * 16 + quad * 4;
;         f32x4 a = acc[nf][mf];
;         if (EPI == EPI_RESID || EPI == EPI_RESID_ATOMIC) {
;           f32x4 x = a;
;           if (EPI == EPI_RESID || kpart == 0) {
;             const u32x2 xr = *(const u32x2*)((const u16*)(p.ws + WS_XB) + (size_t)row * 1024 + col);
;             x[0] += ALPHA * blo(xr[0]); x[1] += ALPHA * bhi(xr[0]); x[2] += ALPHA * blo(xr[1]); x[3] += ALPHA * bhi(xr[1]);
;           }
;           if (EPI == EPI_RESID) *(f32x4*)((float*)(p.ws + WS_XF) + (size_t)row * 1024 + col) = x;
;           else *(f32x4*)((float*)(p.ws + WS_SLAB) + ((size_t)kpart * 512 + (row - T_P)) * 1024 + col) = x;
; DEVI void run_phase(const Params& p, int ph, char* smem) {
;     ...
;       for (int t = xcd_first_tile(); t < 512 + 16 * 2; t += xcd_tile_step()) {
;         if (t < 512) {
;           int mt_, nt_; tile_coords(t, 64, 8, mt_, nt_);
;           gemm_tile256<EPI_RESID>(p, ox, 256, Bt, 256, mt_ * 256, nt_ * 128, nullptr, 0, smem);
;         } else {
;           const int u_ = t - 512, tl_ = u_ / 2, q_ = u_ - tl_ * 2;
;           gemm_tile256<EPI_RESID_ATOMIC>(p, ox, 256, Bt, 256, (64 + (tl_ & 1)) * 256, (tl_ >> 1) * 128, nullptr, 0, smem, q_ * 128, 4, q_);
;         }
	v_permlane16_swap_b32_e32 v192, v194
	v_permlane16_swap_b32_e32 v193, v195
	v_lshlrev_b32_e32 v216, 16, v192
	v_and_b32_e32 v192, 0xffff0000, v192
	v_lshlrev_b32_e32 v217, 16, v193
	v_and_b32_e32 v193, 0xffff0000, v193
	v_fmac_f32_e32 v106, s44, v216
	v_fmac_f32_e32 v107, s44, v192
	v_fmac_f32_e32 v108, s44, v217
	v_fmac_f32_e32 v109, s44, v193
	global_store_dwordx4 v[140:141], v[106:109], off offset:0
	v_lshlrev_b32_e32 v216, 16, v194
	v_and_b32_e32 v194, 0xffff0000, v194
	v_lshlrev_b32_e32 v217, 16, v195
	v_and_b32_e32 v195, 0xffff0000, v195
	v_fmac_f32_e32 v74, s44, v216
	v_fmac_f32_e32 v75, s44, v194
	v_fmac_f32_e32 v76, s44, v217
	v_fmac_f32_e32 v77, s44, v195
	global_store_dwordx4 v[140:141], v[74:77], off offset:64
	s_waitcnt vmcnt(26)
	v_permlane16_swap_b32_e32 v196, v198
	v_permlane16_swap_b32_e32 v197, v199
	v_lshlrev_b32_e32 v216, 16, v196
	v_and_b32_e32 v196, 0xffff0000, v196
	v_lshlrev_b32_e32 v217, 16, v197
	v_and_b32_e32 v197, 0xffff0000, v197
	v_fmac_f32_e32 v42, s44, v216
	v_fmac_f32_e32 v43, s44, v196
	v_fmac_f32_e32 v44, s44, v217
	v_fmac_f32_e32 v45, s44, v197
	global_store_dwordx4 v[140:141], v[42:45], off offset:128
	v_lshlrev_b32_e32 v216, 16, v198
	v_and_b32_e32 v198, 0xffff0000, v198
	v_lshlrev_b32_e32 v217, 16, v199
	v_and_b32_e32 v199, 0xffff0000, v199
	v_fmac_f32_e32 v10, s44, v216
	v_fmac_f32_e32 v11, s44, v198
	v_fmac_f32_e32 v12, s44, v217
	v_fmac_f32_e32 v13, s44, v199
	global_store_dwordx4 v[140:141], v[10:13], off offset:192
	v_lshl_add_u64 v[140:141], v[140:141], 0, s[10:11]
	s_waitcnt vmcnt(27)
	v_permlane16_swap_b32_e32 v200, v202
	v_permlane16_swap_b32_e32 v201, v203
	v_lshlrev_b32_e32 v216, 16, v200
	v_and_b32_e32 v200, 0xffff0000, v200
	v_lshlrev_b32_e32 v217, 16, v201
	v_and_b32_e32 v201, 0xffff0000, v201
	v_fmac_f32_e32 v102, s44, v216
	v_fmac_f32_e32 v103, s44, v200
	v_fmac_f32_e32 v104, s44, v217
	v_fmac_f32_e32 v105, s44, v201
	global_store_dwordx4 v[140:141], v[102:105], off offset:0
	v_lshlrev_b32_e32 v216, 16, v202
	v_and_b32_e32 v202, 0xffff0000, v202
	v_lshlrev_b32_e32 v217, 16, v203
	v_and_b32_e32 v203, 0xffff0000, v203
	v_fmac_f32_e32 v70, s44, v216
	v_fmac_f32_e32 v71, s44, v202
	v_fmac_f32_e32 v72, s44, v217
	v_fmac_f32_e32 v73, s44, v203
	global_store_dwordx4 v[140:141], v[70:73], off offset:64
	s_waitcnt vmcnt(28)
	v_permlane16_swap_b32_e32 v204, v206
	v_permlane16_swap_b32_e32 v205, v207
	v_lshlrev_b32_e32 v216, 16, v204
	v_and_b32_e32 v204, 0xffff0000, v204
	v_lshlrev_b32_e32 v217, 16, v205
	v_and_b32_e32 v205, 0xffff0000, v205
	v_fmac_f32_e32 v38, s44, v216
	v_fmac_f32_e32 v39, s44, v204
	v_fmac_f32_e32 v40, s44, v217
	v_fmac_f32_e32 v41, s44, v205
	global_store_dwordx4 v[140:141], v[38:41], off offset:128
	v_lshlrev_b32_e32 v216, 16, v206
	v_and_b32_e32 v206, 0xffff0000, v206
	v_lshlrev_b32_e32 v217, 16, v207
	v_and_b32_e32 v207, 0xffff0000, v207
	v_fmac_f32_e32 v6, s44, v216
	v_fmac_f32_e32 v7, s44, v206
	v_fmac_f32_e32 v8, s44, v217
	v_fmac_f32_e32 v9, s44, v207
	global_store_dwordx4 v[140:141], v[6:9], off offset:192
	v_lshl_add_u64 v[140:141], v[140:141], 0, s[10:11]
	s_waitcnt vmcnt(29)
	v_permlane16_swap_b32_e32 v208, v210
	v_permlane16_swap_b32_e32 v209, v211
	v_lshlrev_b32_e32 v216, 16, v208
	v_and_b32_e32 v208, 0xffff0000, v208
	v_lshlrev_b32_e32 v217, 16, v209
	v_and_b32_e32 v209, 0xffff0000, v209
	v_fmac_f32_e32 v98, s44, v216
	v_fmac_f32_e32 v99, s44, v208
	v_fmac_f32_e32 v100, s44, v217
	v_fmac_f32_e32 v101, s44, v209
	global_store_dwordx4 v[140:141], v[98:101], off offset:0
	v_lshlrev_b32_e32 v216, 16, v210
	v_and_b32_e32 v210, 0xffff0000, v210
	v_lshlrev_b32_e32 v217, 16, v211
	v_and_b32_e32 v211, 0xffff0000, v211
	v_fmac_f32_e32 v66, s44, v216
	v_fmac_f32_e32 v67, s44, v210
	v_fmac_f32_e32 v68, s44, v217
	v_fmac_f32_e32 v69, s44, v211
	global_store_dwordx4 v[140:141], v[66:69], off offset:64
	s_waitcnt vmcnt(30)
	v_permlane16_swap_b32_e32 v212, v214
	v_permlane16_swap_b32_e32 v213, v215
	v_lshlrev_b32_e32 v216, 16, v212
	v_and_b32_e32 v212, 0xffff0000, v212
	v_lshlrev_b32_e32 v217, 16, v213
	v_and_b32_e32 v213, 0xffff0000, v213
	v_fmac_f32_e32 v34, s44, v216
	v_fmac_f32_e32 v35, s44, v212
	v_fmac_f32_e32 v36, s44, v217
	v_fmac_f32_e32 v37, s44, v213
	global_store_dwordx4 v[140:141], v[34:37], off offset:128
	v_lshlrev_b32_e32 v216, 16, v214
	v_and_b32_e32 v214, 0xffff0000, v214
	v_lshlrev_b32_e32 v217, 16, v215
	v_and_b32_e32 v215, 0xffff0000, v215
	v_fmac_f32_e32 v2, s44, v216
	v_fmac_f32_e32 v3, s44, v214
	v_fmac_f32_e32 v4, s44, v217
	v_fmac_f32_e32 v5, s44, v215
	global_store_dwordx4 v[140:141], v[2:5], off offset:192
	v_readlane_b32 s39, v250, 7
	s_cmpk_lg_u32 s39, 0x200
	s_cbranch_scc1 .LBB0_146
	v_readlane_b32 s40, v250, 0
	s_lshr_b32 s41, s40, 3
	s_and_b32 s40, s40, 7
	s_mul_i32 s40, s40, 4
	s_add_i32 s40, s40, s41
	s_cmp_lt_u32 s41, 4
	s_cselect_b32 s38, s40, 0x4000
	s_branch .LBB0_146

;     ...
;   __syncthreads();
;   G2_STAGE(0); G2_STAGE(1);
;   const int fsw = (0x78 >> (((r16 >> 2) & 3) * 2)) & 3;
;   const int aoff = (wm * 128 + r16) * 64 + ((quad ^ fsw) << 4);
;   const int boff = 16384 + (wn * 64 + r16) * 64 + ((quad ^ fsw) << 4);
;   for (int kt = 0; kt < nk; kt++) {
;     if (kt + 1 < nk) asm volatile("s_waitcnt vmcnt(6)" ::: "memory");
;     else asm volatile("s_waitcnt vmcnt(0)" ::: "memory");
;     __builtin_amdgcn_s_barrier();
;     asm volatile("" ::: "memory");
;     if (kt + 2 < nk) G2_STAGE(kt + 2);
;     const char* cS = smem + (kt % 3) * 24576;
;     bf16x8 xa[8], wb[4];
; #pragma unroll
;     for (int f = 0; f < 8; f++) xa[f] = *(const bf16x8*)(cS + aoff + f * 1024);
; #pragma unroll
;     for (int f = 0; f < 4; f++) wb[f] = *(const bf16x8*)(cS + boff + f * 1024);
; #pragma unroll
;     for (int nf = 0; nf < 4; nf++)
; #pragma unroll
;       for (int mf = 0; mf < 8; mf++)
;         acc[nf][mf] = __builtin_amdgcn_mfma_f32_16x16x32_bf16(wb[nf], xa[mf], acc[nf][mf], 0, 0, 0);
;   }
.Lt4_loop:
	s_waitcnt vmcnt(6) lgkmcnt(0)
	s_barrier
	v_add_u32_e32 v144, s41, v136
	v_mfma_f32_16x16x32_bf16 v[126:129], v[184:187], v[146:149], v[126:129]
	ds_read_b128 v[200:203], v144 offset:0
	v_mfma_f32_16x16x32_bf16 v[122:125], v[184:187], v[152:155], v[122:125]
	ds_read_b128 v[204:207], v144 offset:1024
	v_mfma_f32_16x16x32_bf16 v[118:121], v[184:187], v[156:159], v[118:121]
	ds_read_b128 v[208:211], v144 offset:2048
	v_mfma_f32_16x16x32_bf16 v[114:117], v[184:187], v[162:165], v[114:117]
	ds_read_b128 v[212:215], v144 offset:3072
	v_mfma_f32_16x16x32_bf16 v[110:113], v[184:187], v[166:169], v[110:113]
	ds_read_b128 v[216:219], v144 offset:4096
	v_mfma_f32_16x16x32_bf16 v[106:109], v[184:187], v[170:173], v[106:109]
	ds_read_b128 v[220:223], v144 offset:5120
	v_mfma_f32_16x16x32_bf16 v[102:105], v[184:187], v[176:179], v[102:105]
	ds_read_b128 v[224:227], v144 offset:6144
	v_mfma_f32_16x16x32_bf16 v[98:101], v[184:187], v[180:183], v[98:101]
	ds_read_b128 v[228:231], v144 offset:7168
	v_mfma_f32_16x16x32_bf16 v[94:97], v[188:191], v[146:149], v[94:97]
	v_add_u32_e32 v144, s41, v137
	v_mfma_f32_16x16x32_bf16 v[90:93], v[188:191], v[152:155], v[90:93]
	v_mfma_f32_16x16x32_bf16 v[86:89], v[188:191], v[156:159], v[86:89]
	ds_read_b128 v[232:235], v144 offset:16384
	v_mfma_f32_16x16x32_bf16 v[82:85], v[188:191], v[162:165], v[82:85]
	ds_read_b128 v[236:239], v144 offset:17408
	v_mfma_f32_16x16x32_bf16 v[78:81], v[188:191], v[166:169], v[78:81]
	ds_read_b128 v[240:243], v144 offset:18432
	v_mfma_f32_16x16x32_bf16 v[74:77], v[188:191], v[170:173], v[74:77]
	ds_read_b128 v[244:247], v144 offset:19456
	s_add_i32 s43, s47, s42
	v_mfma_f32_16x16x32_bf16 v[70:73], v[188:191], v[176:179], v[70:73]
	s_mov_b32 m0, s43
	v_lshl_add_u64 v[142:143], v[132:133], 0, s[2:3]
	v_mfma_f32_16x16x32_bf16 v[66:69], v[188:191], v[180:183], v[66:69]
	global_load_lds_dwordx4 v[132:133], off
	s_addk_i32 m0, 0x1000
	v_mfma_f32_16x16x32_bf16 v[62:65], v[192:195], v[146:149], v[62:65]
	v_mfma_f32_16x16x32_bf16 v[58:61], v[192:195], v[152:155], v[58:61]
	v_mfma_f32_16x16x32_bf16 v[54:57], v[192:195], v[156:159], v[54:57]
	global_load_lds_dwordx4 v[142:143], off
	v_lshl_add_u64 v[142:143], v[142:143], 0, s[2:3]
	s_addk_i32 m0, 0x1000
	v_mfma_f32_16x16x32_bf16 v[50:53], v[192:195], v[162:165], v[50:53]
	v_mfma_f32_16x16x32_bf16 v[46:49], v[192:195], v[166:169], v[46:49]
	v_mfma_f32_16x16x32_bf16 v[42:45], v[192:195], v[170:173], v[42:45]
	global_load_lds_dwordx4 v[142:143], off
	v_lshl_add_u64 v[142:143], v[142:143], 0, s[2:3]
	s_addk_i32 m0, 0x1000
	v_mfma_f32_16x16x32_bf16 v[38:41], v[192:195], v[176:179], v[38:41]
	v_mfma_f32_16x16x32_bf16 v[34:37], v[192:195], v[180:183], v[34:37]
	v_mfma_f32_16x16x32_bf16 v[30:33], v[196:199], v[146:149], v[30:33]
	global_load_lds_dwordx4 v[142:143], off
	s_addk_i32 m0, 0x1000
	v_lshl_add_u64 v[142:143], v[134:135], 0, s[2:3]
	v_mfma_f32_16x16x32_bf16 v[26:29], v[196:199], v[152:155], v[26:29]
	v_mfma_f32_16x16x32_bf16 v[22:25], v[196:199], v[156:159], v[22:25]
	v_mfma_f32_16x16x32_bf16 v[18:21], v[196:199], v[162:165], v[18:21]
	global_load_lds_dwordx4 v[134:135], off
	s_addk_i32 m0, 0x1000
	v_lshl_add_u64 v[132:133], v[132:133], 0, s[12:13]
	v_mfma_f32_16x16x32_bf16 v[14:17], v[196:199], v[166:169], v[14:17]
	v_mfma_f32_16x16x32_bf16 v[10:13], v[196:199], v[170:173], v[10:13]
	v_mfma_f32_16x16x32_bf16 v[6:9], v[196:199], v[176:179], v[6:9]
	global_load_lds_dwordx4 v[142:143], off
	v_lshl_add_u64 v[134:135], v[134:135], 0, s[4:5]
	v_mfma_f32_16x16x32_bf16 v[2:5], v[196:199], v[180:183], v[2:5]
	s_mov_b32 s42, s41
	s_add_i32 s41, s41, 0x6000
	s_cmp_eq_u32 s41, 0x12000
	s_cselect_b32 s41, 0, s41
	s_waitcnt vmcnt(6) lgkmcnt(0)
	s_barrier
	v_add_u32_e32 v144, s41, v136
	v_mfma_f32_16x16x32_bf16 v[126:129], v[232:235], v[200:203], v[126:129]
	ds_read_b128 v[146:149], v144 offset:0
	v_mfma_f32_16x16x32_bf16 v[122:125], v[232:235], v[204:207], v[122:125]
	ds_read_b128 v[152:155], v144 offset:1024
	v_mfma_f32_16x16x32_bf16 v[118:121], v[232:235], v[208:211], v[118:121]
	ds_read_b128 v[156:159], v144 offset:2048
	v_mfma_f32_16x16x32_bf16 v[114:117], v[232:235], v[212:215], v[114:117]
	ds_read_b128 v[162:165], v144 offset:3072
	v_mfma_f32_16x16x32_bf16 v[110:113], v[232:235], v[216:219], v[110:113]
	ds_read_b128 v[166:169], v144 offset:4096
	v_mfma_f32_16x16x32_bf16 v[106:109], v[232:235], v[220:223], v[106:109]
	ds_read_b128 v[170:173], v144 offset:5120
	v_mfma_f32_16x16x32_bf16 v[102:105], v[232:235], v[224:227], v[102:105]
	ds_read_b128 v[176:179], v144 offset:6144
	v_mfma_f32_16x16x32_bf16 v[98:101], v[232:235], v[228:231], v[98:101]
	ds_read_b128 v[180:183], v144 offset:7168
	v_mfma_f32_16x16x32_bf16 v[94:97], v[236:239], v[200:203], v[94:97]
	v_add_u32_e32 v144, s41, v137
	v_mfma_f32_16x16x32_bf16 v[90:93], v[236:239], v[204:207], v[90:93]
	v_mfma_f32_16x16x32_bf16 v[86:89], v[236:239], v[208:211], v[86:89]
	ds_read_b128 v[184:187], v144 offset:16384
	v_mfma_f32_16x16x32_bf16 v[82:85], v[236:239], v[212:215], v[82:85]
	ds_read_b128 v[188:191], v144 offset:17408
	v_mfma_f32_16x16x32_bf16 v[78:81], v[236:239], v[216:219], v[78:81]
	ds_read_b128 v[192:195], v144 offset:18432
	v_mfma_f32_16x16x32_bf16 v[74:77], v[236:239], v[220:223], v[74:77]
	ds_read_b128 v[196:199], v144 offset:19456
	s_add_i32 s43, s47, s42
	v_mfma_f32_16x16x32_bf16 v[70:73], v[236:239], v[224:227], v[70:73]
	s_mov_b32 m0, s43
	v_lshl_add_u64 v[142:143], v[132:133], 0, s[2:3]
	v_mfma_f32_16x16x32_bf16 v[66:69], v[236:239], v[228:231], v[66:69]
	global_load_lds_dwordx4 v[132:133], off
	s_addk_i32 m0, 0x1000
	v_mfma_f32_16x16x32_bf16 v[62:65], v[240:243], v[200:203], v[62:65]
;     ...
;   __syncthreads();
;   G2_STAGE(0); G2_STAGE(1);
;   const int fsw = (0x78 >> (((r16 >> 2) & 3) * 2)) & 3;
;   const int aoff = (wm * 128 + r16) * 64 + ((quad ^ fsw) << 4);
;   const int boff = 16384 + (wn * 64 + r16) * 64 + ((quad ^ fsw) << 4);
;   for (int kt = 0; kt < nk; kt++) {
;     if (kt + 1 < nk) asm volatile("s_waitcnt vmcnt(6)" ::: "memory");
;     else asm volatile("s_waitcnt vmcnt(0)" ::: "memory");
;     __builtin_amdgcn_s_barrier();
;     asm volatile("" ::: "memory");
;     if (kt + 2 < nk) G2_STAGE(kt + 2);
;     const char* cS = smem + (kt % 3) * 24576;
;     bf16x8 xa[8], wb[4];
; #pragma unroll
;     for (int f = 0; f < 8; f++) xa[f] = *(const bf16x8*)(cS + aoff + f * 1024);
; #pragma unroll
;     for (int f = 0; f < 4; f++) wb[f] = *(const bf16x8*)(cS + boff + f * 1024);
; #pragma unroll
;     for (int nf = 0; nf < 4; nf++)
; #pragma unroll
;       for (int mf = 0; mf < 8; mf++)
;         acc[nf][mf] = __builtin_amdgcn_mfma_f32_16x16x32_bf16(wb[nf], xa[mf], acc[nf][mf], 0, 0, 0);
;   }
	v_mfma_f32_16x16x32_bf16 v[58:61], v[240:243], v[204:207], v[58:61]
	v_mfma_f32_16x16x32_bf16 v[54:57], v[240:243], v[208:211], v[54:57]
	global_load_lds_dwordx4 v[142:143], off
	v_lshl_add_u64 v[142:143], v[142:143], 0, s[2:3]
	s_addk_i32 m0, 0x1000
	v_mfma_f32_16x16x32_bf16 v[50:53], v[240:243], v[212:215], v[50:53]
	v_mfma_f32_16x16x32_bf16 v[46:49], v[240:243], v[216:219], v[46:49]
	v_mfma_f32_16x16x32_bf16 v[42:45], v[240:243], v[220:223], v[42:45]
	global_load_lds_dwordx4 v[142:143], off
	v_lshl_add_u64 v[142:143], v[142:143], 0, s[2:3]
	s_addk_i32 m0, 0x1000
	v_mfma_f32_16x16x32_bf16 v[38:41], v[240:243], v[224:227], v[38:41]
	v_mfma_f32_16x16x32_bf16 v[34:37], v[240:243], v[228:231], v[34:37]
	v_mfma_f32_16x16x32_bf16 v[30:33], v[244:247], v[200:203], v[30:33]
	global_load_lds_dwordx4 v[142:143], off
	s_addk_i32 m0, 0x1000
	v_lshl_add_u64 v[142:143], v[134:135], 0, s[2:3]
	v_mfma_f32_16x16x32_bf16 v[26:29], v[244:247], v[204:207], v[26:29]
	v_mfma_f32_16x16x32_bf16 v[22:25], v[244:247], v[208:211], v[22:25]
	v_mfma_f32_16x16x32_bf16 v[18:21], v[244:247], v[212:215], v[18:21]
	global_load_lds_dwordx4 v[134:135], off
	s_addk_i32 m0, 0x1000
	v_lshl_add_u64 v[132:133], v[132:133], 0, s[12:13]
	v_mfma_f32_16x16x32_bf16 v[14:17], v[244:247], v[216:219], v[14:17]
	v_mfma_f32_16x16x32_bf16 v[10:13], v[244:247], v[220:223], v[10:13]
	v_mfma_f32_16x16x32_bf16 v[6:9], v[244:247], v[224:227], v[6:9]
	global_load_lds_dwordx4 v[142:143], off
	v_lshl_add_u64 v[134:135], v[134:135], 0, s[4:5]
	v_mfma_f32_16x16x32_bf16 v[2:5], v[244:247], v[228:231], v[2:5]
	s_mov_b32 s42, s41
	s_add_i32 s41, s41, 0x6000
	s_cmp_eq_u32 s41, 0x12000
	s_cselect_b32 s41, 0, s41
	s_sub_i32 s40, s40, 1
	s_cmp_lg_u32 s40, 0
	s_cbranch_scc1 .Lt4_loop
	s_waitcnt vmcnt(6) lgkmcnt(0)
	s_barrier
	v_add_u32_e32 v144, s41, v136
	v_mfma_f32_16x16x32_bf16 v[126:129], v[184:187], v[146:149], v[126:129]
	ds_read_b128 v[200:203], v144 offset:0
	v_mfma_f32_16x16x32_bf16 v[122:125], v[184:187], v[152:155], v[122:125]
	ds_read_b128 v[204:207], v144 offset:1024
	v_mfma_f32_16x16x32_bf16 v[118:121], v[184:187], v[156:159], v[118:121]
	ds_read_b128 v[208:211], v144 offset:2048
	v_mfma_f32_16x16x32_bf16 v[114:117], v[184:187], v[162:165], v[114:117]
	ds_read_b128 v[212:215], v144 offset:3072
	v_mfma_f32_16x16x32_bf16 v[110:113], v[184:187], v[166:169], v[110:113]
	ds_read_b128 v[216:219], v144 offset:4096
	v_mfma_f32_16x16x32_bf16 v[106:109], v[184:187], v[170:173], v[106:109]
	ds_read_b128 v[220:223], v144 offset:5120
	v_mfma_f32_16x16x32_bf16 v[102:105], v[184:187], v[176:179], v[102:105]
	ds_read_b128 v[224:227], v144 offset:6144
	v_mfma_f32_16x16x32_bf16 v[98:101], v[184:187], v[180:183], v[98:101]
	ds_read_b128 v[228:231], v144 offset:7168
	v_mfma_f32_16x16x32_bf16 v[94:97], v[188:191], v[146:149], v[94:97]
	v_add_u32_e32 v144, s41, v137
	v_mfma_f32_16x16x32_bf16 v[90:93], v[188:191], v[152:155], v[90:93]
	v_mfma_f32_16x16x32_bf16 v[86:89], v[188:191], v[156:159], v[86:89]
	ds_read_b128 v[232:235], v144 offset:16384
	v_mfma_f32_16x16x32_bf16 v[82:85], v[188:191], v[162:165], v[82:85]
	ds_read_b128 v[236:239], v144 offset:17408
	v_mfma_f32_16x16x32_bf16 v[78:81], v[188:191], v[166:169], v[78:81]
	ds_read_b128 v[240:243], v144 offset:18432
	v_mfma_f32_16x16x32_bf16 v[74:77], v[188:191], v[170:173], v[74:77]
	ds_read_b128 v[244:247], v144 offset:19456
	s_add_i32 s43, s47, s42
	v_mfma_f32_16x16x32_bf16 v[70:73], v[188:191], v[176:179], v[70:73]
	s_mov_b32 m0, s43
	v_lshl_add_u64 v[142:143], v[132:133], 0, s[2:3]
	v_mfma_f32_16x16x32_bf16 v[66:69], v[188:191], v[180:183], v[66:69]
	global_load_lds_dwordx4 v[132:133], off
	s_addk_i32 m0, 0x1000
	v_mfma_f32_16x16x32_bf16 v[62:65], v[192:195], v[146:149], v[62:65]
	v_mfma_f32_16x16x32_bf16 v[58:61], v[192:195], v[152:155], v[58:61]
	v_mfma_f32_16x16x32_bf16 v[54:57], v[192:195], v[156:159], v[54:57]
	global_load_lds_dwordx4 v[142:143], off
	v_lshl_add_u64 v[142:143], v[142:143], 0, s[2:3]
	s_addk_i32 m0, 0x1000
	v_mfma_f32_16x16x32_bf16 v[50:53], v[192:195], v[162:165], v[50:53]
	v_mfma_f32_16x16x32_bf16 v[46:49], v[192:195], v[166:169], v[46:49]
	v_mfma_f32_16x16x32_bf16 v[42:45], v[192:195], v[170:173], v[42:45]
	global_load_lds_dwordx4 v[142:143], off
	v_lshl_add_u64 v[142:143], v[142:143], 0, s[2:3]
	s_addk_i32 m0, 0x1000
	v_mfma_f32_16x16x32_bf16 v[38:41], v[192:195], v[176:179], v[38:41]
	v_mfma_f32_16x16x32_bf16 v[34:37], v[192:195], v[180:183], v[34:37]
	v_mfma_f32_16x16x32_bf16 v[30:33], v[196:199], v[146:149], v[30:33]
	global_load_lds_dwordx4 v[142:143], off
	s_addk_i32 m0, 0x1000
	v_lshl_add_u64 v[142:143], v[134:135], 0, s[2:3]
	v_mfma_f32_16x16x32_bf16 v[26:29], v[196:199], v[152:155], v[26:29]
	v_mfma_f32_16x16x32_bf16 v[22:25], v[196:199], v[156:159], v[22:25]
	v_mfma_f32_16x16x32_bf16 v[18:21], v[196:199], v[162:165], v[18:21]
	global_load_lds_dwordx4 v[134:135], off
	s_addk_i32 m0, 0x1000
	v_lshl_add_u64 v[132:133], v[132:133], 0, s[12:13]
	v_mfma_f32_16x16x32_bf16 v[14:17], v[196:199], v[166:169], v[14:17]
	v_mfma_f32_16x16x32_bf16 v[10:13], v[196:199], v[170:173], v[10:13]
	v_mfma_f32_16x16x32_bf16 v[6:9], v[196:199], v[176:179], v[6:9]
	global_load_lds_dwordx4 v[142:143], off
	v_lshl_add_u64 v[134:135], v[134:135], 0, s[4:5]
	v_mfma_f32_16x16x32_bf16 v[2:5], v[196:199], v[180:183], v[2:5]
	s_mov_b32 s42, s41
	s_add_i32 s41, s41, 0x6000
	s_cmp_eq_u32 s41, 0x12000
	s_cselect_b32 s41, 0, s41
	s_waitcnt vmcnt(6) lgkmcnt(0)
	s_barrier
;     ...
;   for (int kt = 0; kt < nk; kt++) {
;     if (kt + 1 < nk) asm volatile("s_waitcnt vmcnt(6)" ::: "memory");
;     else asm volatile("s_waitcnt vmcnt(0)" ::: "memory");
;     __builtin_amdgcn_s_barrier();
;     asm volatile("" ::: "memory");
;     if (kt + 2 < nk) G2_STAGE(kt + 2);
;     const char* cS = smem + (kt % 3) * 24576;
;     bf16x8 xa[8], wb[4];
; #pragma unroll
;     for (int f = 0; f < 8; f++) xa[f] = *(const bf16x8*)(cS + aoff + f * 1024);
; #pragma unroll
;     for (int f = 0; f < 4; f++) wb[f] = *(const bf16x8*)(cS + boff + f * 1024);
; #pragma unroll
;     for (int nf = 0; nf < 4; nf++)
; #pragma unroll
;       for (int mf = 0; mf < 8; mf++)
;         acc[nf][mf] = __builtin_amdgcn_mfma_f32_16x16x32_bf16(wb[nf], xa[mf], acc[nf][mf], 0, 0, 0);
;   }
	v_add_u32_e32 v144, s41, v136
	v_mfma_f32_16x16x32_bf16 v[126:129], v[232:235], v[200:203], v[126:129]
	ds_read_b128 v[146:149], v144 offset:0
	v_mfma_f32_16x16x32_bf16 v[122:125], v[232:235], v[204:207], v[122:125]
	ds_read_b128 v[152:155], v144 offset:1024
	v_mfma_f32_16x16x32_bf16 v[118:121], v[232:235], v[208:211], v[118:121]
	ds_read_b128 v[156:159], v144 offset:2048
	v_mfma_f32_16x16x32_bf16 v[114:117], v[232:235], v[212:215], v[114:117]
	ds_read_b128 v[162:165], v144 offset:3072
	v_mfma_f32_16x16x32_bf16 v[110:113], v[232:235], v[216:219], v[110:113]
	ds_read_b128 v[166:169], v144 offset:4096
	v_mfma_f32_16x16x32_bf16 v[106:109], v[232:235], v[220:223], v[106:109]
	ds_read_b128 v[170:173], v144 offset:5120
	v_mfma_f32_16x16x32_bf16 v[102:105], v[232:235], v[224:227], v[102:105]
	ds_read_b128 v[176:179], v144 offset:6144
	v_mfma_f32_16x16x32_bf16 v[98:101], v[232:235], v[228:231], v[98:101]
	ds_read_b128 v[180:183], v144 offset:7168
	v_mfma_f32_16x16x32_bf16 v[94:97], v[236:239], v[200:203], v[94:97]
	v_add_u32_e32 v144, s41, v137
	v_mfma_f32_16x16x32_bf16 v[90:93], v[236:239], v[204:207], v[90:93]
	v_mfma_f32_16x16x32_bf16 v[86:89], v[236:239], v[208:211], v[86:89]
	ds_read_b128 v[184:187], v144 offset:16384
	v_mfma_f32_16x16x32_bf16 v[82:85], v[236:239], v[212:215], v[82:85]
	ds_read_b128 v[188:191], v144 offset:17408
	v_mfma_f32_16x16x32_bf16 v[78:81], v[236:239], v[216:219], v[78:81]
	ds_read_b128 v[192:195], v144 offset:18432
	v_mfma_f32_16x16x32_bf16 v[74:77], v[236:239], v[220:223], v[74:77]
	ds_read_b128 v[196:199], v144 offset:19456
	v_mfma_f32_16x16x32_bf16 v[70:73], v[236:239], v[224:227], v[70:73]
	v_mfma_f32_16x16x32_bf16 v[66:69], v[236:239], v[228:231], v[66:69]
	v_mfma_f32_16x16x32_bf16 v[62:65], v[240:243], v[200:203], v[62:65]
	v_mfma_f32_16x16x32_bf16 v[58:61], v[240:243], v[204:207], v[58:61]
	v_mfma_f32_16x16x32_bf16 v[54:57], v[240:243], v[208:211], v[54:57]
	v_mfma_f32_16x16x32_bf16 v[50:53], v[240:243], v[212:215], v[50:53]
	v_mfma_f32_16x16x32_bf16 v[46:49], v[240:243], v[216:219], v[46:49]
	v_mfma_f32_16x16x32_bf16 v[42:45], v[240:243], v[220:223], v[42:45]
	v_mfma_f32_16x16x32_bf16 v[38:41], v[240:243], v[224:227], v[38:41]
	v_mfma_f32_16x16x32_bf16 v[34:37], v[240:243], v[228:231], v[34:37]
	v_mfma_f32_16x16x32_bf16 v[30:33], v[244:247], v[200:203], v[30:33]
	v_mfma_f32_16x16x32_bf16 v[26:29], v[244:247], v[204:207], v[26:29]
	v_mfma_f32_16x16x32_bf16 v[22:25], v[244:247], v[208:211], v[22:25]
	v_mfma_f32_16x16x32_bf16 v[18:21], v[244:247], v[212:215], v[18:21]
	v_mfma_f32_16x16x32_bf16 v[14:17], v[244:247], v[216:219], v[14:17]
	v_mfma_f32_16x16x32_bf16 v[10:13], v[244:247], v[220:223], v[10:13]
	v_mfma_f32_16x16x32_bf16 v[6:9], v[244:247], v[224:227], v[6:9]
	v_mfma_f32_16x16x32_bf16 v[2:5], v[244:247], v[228:231], v[2:5]
	s_mov_b32 s42, s41
	s_add_i32 s41, s41, 0x6000
	s_cmp_eq_u32 s41, 0x12000
	s_cselect_b32 s41, 0, s41
	s_waitcnt vmcnt(0) lgkmcnt(0)
	s_barrier
	v_add_u32_e32 v144, s41, v136
	v_mfma_f32_16x16x32_bf16 v[126:129], v[184:187], v[146:149], v[126:129]
	ds_read_b128 v[200:203], v144 offset:0
	v_mfma_f32_16x16x32_bf16 v[122:125], v[184:187], v[152:155], v[122:125]
	ds_read_b128 v[204:207], v144 offset:1024
	v_mfma_f32_16x16x32_bf16 v[118:121], v[184:187], v[156:159], v[118:121]
	ds_read_b128 v[208:211], v144 offset:2048
	v_mfma_f32_16x16x32_bf16 v[114:117], v[184:187], v[162:165], v[114:117]
	ds_read_b128 v[212:215], v144 offset:3072
	v_mfma_f32_16x16x32_bf16 v[110:113], v[184:187], v[166:169], v[110:113]
	ds_read_b128 v[216:219], v144 offset:4096
	v_mfma_f32_16x16x32_bf16 v[106:109], v[184:187], v[170:173], v[106:109]
	ds_read_b128 v[220:223], v144 offset:5120
	v_mfma_f32_16x16x32_bf16 v[102:105], v[184:187], v[176:179], v[102:105]
	ds_read_b128 v[224:227], v144 offset:6144
	v_mfma_f32_16x16x32_bf16 v[98:101], v[184:187], v[180:183], v[98:101]
	ds_read_b128 v[228:231], v144 offset:7168
	v_mfma_f32_16x16x32_bf16 v[94:97], v[188:191], v[146:149], v[94:97]
	v_add_u32_e32 v144, s41, v137
	v_mfma_f32_16x16x32_bf16 v[90:93], v[188:191], v[152:155], v[90:93]
	v_mfma_f32_16x16x32_bf16 v[86:89], v[188:191], v[156:159], v[86:89]
	ds_read_b128 v[232:235], v144 offset:16384
	v_mfma_f32_16x16x32_bf16 v[82:85], v[188:191], v[162:165], v[82:85]
	ds_read_b128 v[236:239], v144 offset:17408
	v_mfma_f32_16x16x32_bf16 v[78:81], v[188:191], v[166:169], v[78:81]
	ds_read_b128 v[240:243], v144 offset:18432
	v_mfma_f32_16x16x32_bf16 v[74:77], v[188:191], v[170:173], v[74:77]
	ds_read_b128 v[244:247], v144 offset:19456
	v_mfma_f32_16x16x32_bf16 v[70:73], v[188:191], v[176:179], v[70:73]
	v_mfma_f32_16x16x32_bf16 v[66:69], v[188:191], v[180:183], v[66:69]
	v_mfma_f32_16x16x32_bf16 v[62:65], v[192:195], v[146:149], v[62:65]
	v_mfma_f32_16x16x32_bf16 v[58:61], v[192:195], v[152:155], v[58:61]
	v_mfma_f32_16x16x32_bf16 v[54:57], v[192:195], v[156:159], v[54:57]
	v_mfma_f32_16x16x32_bf16 v[50:53], v[192:195], v[162:165], v[50:53]
	v_mfma_f32_16x16x32_bf16 v[46:49], v[192:195], v[166:169], v[46:49]
	v_mfma_f32_16x16x32_bf16 v[42:45], v[192:195], v[170:173], v[42:45]
	v_mfma_f32_16x16x32_bf16 v[38:41], v[192:195], v[176:179], v[38:41]
	v_mfma_f32_16x16x32_bf16 v[34:37], v[192:195], v[180:183], v[34:37]
	v_mfma_f32_16x16x32_bf16 v[30:33], v[196:199], v[146:149], v[30:33]
	v_mfma_f32_16x16x32_bf16 v[26:29], v[196:199], v[152:155], v[26:29]
	v_mfma_f32_16x16x32_bf16 v[22:25], v[196:199], v[156:159], v[22:25]
	v_mfma_f32_16x16x32_bf16 v[18:21], v[196:199], v[162:165], v[18:21]
	v_mfma_f32_16x16x32_bf16 v[14:17], v[196:199], v[166:169], v[14:17]
	v_mfma_f32_16x16x32_bf16 v[10:13], v[196:199], v[170:173], v[10:13]
	v_mfma_f32_16x16x32_bf16 v[6:9], v[196:199], v[176:179], v[6:9]
	v_mfma_f32_16x16x32_bf16 v[2:5], v[196:199], v[180:183], v[2:5]
	s_mov_b32 s42, s41
	s_add_i32 s41, s41, 0x6000
	s_cmp_eq_u32 s41, 0x12000
	s_cselect_b32 s41, 0, s41
	s_mov_b32 s4, 0x8000
	s_mov_b32 s5, 0
	s_mov_b32 s10, 0x10000
	s_mov_b32 s11, 0
	s_mov_b32 s45, 0x3fd744fd
	s_waitcnt lgkmcnt(0)
; DEVI float blo(unsigned u) { return __uint_as_float(u << 16); }
; DEVI float bhi(unsigned u) { return __uint_as_float(u & 0xffff0000u); }
;     ...
;   for (int kt = 0; kt < nk; kt++) {
;     if (kt + 1 < nk) asm volatile("s_waitcnt vmcnt(6)" ::: "memory");
;     else asm volatile("s_waitcnt vmcnt(0)" ::: "memory");
;     __builtin_amdgcn_s_barrier();
;     asm volatile("" ::: "memory");
;     if (kt + 2 < nk) G2_STAGE(kt + 2);
;     const char* cS = smem + (kt % 3) * 24576;
;     bf16x8 xa[8], wb[4];
; #pragma unroll
;     for (int f = 0; f < 8; f++) xa[f] = *(const bf16x8*)(cS + aoff + f * 1024);
; #pragma unroll
;     for (int f = 0; f < 4; f++) wb[f] = *(const bf16x8*)(cS + boff + f * 1024);
; #pragma unroll
;     for (int nf = 0; nf < 4; nf++)
; #pragma unroll
;       for (int mf = 0; mf < 8; mf++)
;         acc[nf][mf] = __builtin_amdgcn_mfma_f32_16x16x32_bf16(wb[nf], xa[mf], acc[nf][mf], 0, 0, 0);
;   }
;     ...
; #pragma unroll
;       for (int nf = 0; nf < 4; nf++) {
;         const int col = n0 + wn * 64 + nf * 16 + quad * 4;
;         f32x4 a = acc[nf][mf];
;         if (EPI == EPI_RESID || EPI == EPI_RESID_ATOMIC) {
;           f32x4 x = a;
;           if (EPI == EPI_RESID || kpart == 0) {
;             const u32x2 xr = *(const u32x2*)((const u16*)(p.ws + WS_XB) + (size_t)row * 1024 + col);
;             x[0] += ALPHA * blo(xr[0]); x[1] += ALPHA * bhi(xr[0]); x[2] += ALPHA * blo(xr[1]); x[3] += ALPHA * bhi(xr[1]);
;           }
;           if (EPI == EPI_RESID) *(f32x4*)((float*)(p.ws + WS_XF) + (size_t)row * 1024 + col) = x;
;           else *(f32x4*)((float*)(p.ws + WS_SLAB) + ((size_t)kpart * 512 + (row - T_P)) * 1024 + col) = x;
	v_mfma_f32_16x16x32_bf16 v[126:129], v[232:235], v[200:203], v[126:129]
	v_mfma_f32_16x16x32_bf16 v[122:125], v[232:235], v[204:207], v[122:125]
	v_mfma_f32_16x16x32_bf16 v[118:121], v[232:235], v[208:211], v[118:121]
	v_mfma_f32_16x16x32_bf16 v[114:117], v[232:235], v[212:215], v[114:117]
	v_mfma_f32_16x16x32_bf16 v[110:113], v[232:235], v[216:219], v[110:113]
	global_load_dwordx4 v[146:149], v[138:139], off offset:0
	v_mfma_f32_16x16x32_bf16 v[106:109], v[232:235], v[220:223], v[106:109]
	v_mfma_f32_16x16x32_bf16 v[102:105], v[232:235], v[224:227], v[102:105]
	global_load_dwordx4 v[152:155], v[138:139], off offset:128
	v_mfma_f32_16x16x32_bf16 v[98:101], v[232:235], v[228:231], v[98:101]
	v_lshl_add_u64 v[138:139], v[138:139], 0, s[4:5]
	v_mfma_f32_16x16x32_bf16 v[94:97], v[236:239], v[200:203], v[94:97]
	global_load_dwordx4 v[156:159], v[138:139], off offset:0
	v_mfma_f32_16x16x32_bf16 v[90:93], v[236:239], v[204:207], v[90:93]
	v_mfma_f32_16x16x32_bf16 v[86:89], v[236:239], v[208:211], v[86:89]
	global_load_dwordx4 v[162:165], v[138:139], off offset:128
	v_mfma_f32_16x16x32_bf16 v[82:85], v[236:239], v[212:215], v[82:85]
	v_lshl_add_u64 v[138:139], v[138:139], 0, s[4:5]
	v_mfma_f32_16x16x32_bf16 v[78:81], v[236:239], v[216:219], v[78:81]
	global_load_dwordx4 v[166:169], v[138:139], off offset:0
	v_mfma_f32_16x16x32_bf16 v[74:77], v[236:239], v[220:223], v[74:77]
	v_mfma_f32_16x16x32_bf16 v[70:73], v[236:239], v[224:227], v[70:73]
	global_load_dwordx4 v[170:173], v[138:139], off offset:128
	v_mfma_f32_16x16x32_bf16 v[66:69], v[236:239], v[228:231], v[66:69]
	v_lshl_add_u64 v[138:139], v[138:139], 0, s[4:5]
	v_mfma_f32_16x16x32_bf16 v[62:65], v[240:243], v[200:203], v[62:65]
	global_load_dwordx4 v[176:179], v[138:139], off offset:0
	v_mfma_f32_16x16x32_bf16 v[58:61], v[240:243], v[204:207], v[58:61]
	v_mfma_f32_16x16x32_bf16 v[54:57], v[240:243], v[208:211], v[54:57]
	global_load_dwordx4 v[180:183], v[138:139], off offset:128
	v_mfma_f32_16x16x32_bf16 v[50:53], v[240:243], v[212:215], v[50:53]
	v_lshl_add_u64 v[138:139], v[138:139], 0, s[4:5]
	v_mfma_f32_16x16x32_bf16 v[46:49], v[240:243], v[216:219], v[46:49]
	global_load_dwordx4 v[184:187], v[138:139], off offset:0
	v_mfma_f32_16x16x32_bf16 v[42:45], v[240:243], v[220:223], v[42:45]
	v_mfma_f32_16x16x32_bf16 v[38:41], v[240:243], v[224:227], v[38:41]
	global_load_dwordx4 v[188:191], v[138:139], off offset:128
	v_mfma_f32_16x16x32_bf16 v[34:37], v[240:243], v[228:231], v[34:37]
	v_lshl_add_u64 v[138:139], v[138:139], 0, s[4:5]
	v_mfma_f32_16x16x32_bf16 v[30:33], v[244:247], v[200:203], v[30:33]
	global_load_dwordx4 v[192:195], v[138:139], off offset:0
	v_mfma_f32_16x16x32_bf16 v[26:29], v[244:247], v[204:207], v[26:29]
	v_mfma_f32_16x16x32_bf16 v[22:25], v[244:247], v[208:211], v[22:25]
	global_load_dwordx4 v[196:199], v[138:139], off offset:128
	v_mfma_f32_16x16x32_bf16 v[18:21], v[244:247], v[212:215], v[18:21]
	v_lshl_add_u64 v[138:139], v[138:139], 0, s[4:5]
	v_mfma_f32_16x16x32_bf16 v[14:17], v[244:247], v[216:219], v[14:17]
	v_mfma_f32_16x16x32_bf16 v[10:13], v[244:247], v[220:223], v[10:13]
	v_mfma_f32_16x16x32_bf16 v[6:9], v[244:247], v[224:227], v[6:9]
	v_mfma_f32_16x16x32_bf16 v[2:5], v[244:247], v[228:231], v[2:5]
	s_mov_b32 m0, s44
	global_load_dwordx4 v[200:203], v[138:139], off offset:0
	global_load_dwordx4 v[204:207], v[138:139], off offset:128
	v_lshl_add_u64 v[138:139], v[138:139], 0, s[4:5]
	global_load_dwordx4 v[208:211], v[138:139], off offset:0
	global_load_dwordx4 v[212:215], v[138:139], off offset:128
	v_lshl_add_u64 v[138:139], v[138:139], 0, s[4:5]
	s_nop 7
	s_waitcnt vmcnt(15)
	v_permlane16_swap_b32_e32 v146, v148
	v_permlane16_swap_b32_e32 v147, v149
	v_lshlrev_b32_e32 v216, 16, v146
	v_and_b32_e32 v146, 0xffff0000, v146
	v_lshlrev_b32_e32 v217, 16, v147
	v_and_b32_e32 v147, 0xffff0000, v147
	v_fmac_f32_e32 v126, s45, v216
	v_fmac_f32_e32 v127, s45, v146
	v_fmac_f32_e32 v128, s45, v217
	v_fmac_f32_e32 v129, s45, v147
	global_store_dwordx4 v[140:141], v[126:129], off offset:0
	v_lshlrev_b32_e32 v216, 16, v148
	v_and_b32_e32 v148, 0xffff0000, v148
	v_lshlrev_b32_e32 v217, 16, v149
	v_and_b32_e32 v149, 0xffff0000, v149
	v_fmac_f32_e32 v94, s45, v216
	v_fmac_f32_e32 v95, s45, v148
	v_fmac_f32_e32 v96, s45, v217
	v_fmac_f32_e32 v97, s45, v149
	global_store_dwordx4 v[140:141], v[94:97], off offset:64
	s_waitcnt vmcnt(16)
	v_permlane16_swap_b32_e32 v152, v154
	v_permlane16_swap_b32_e32 v153, v155
	v_lshlrev_b32_e32 v216, 16, v152
	v_and_b32_e32 v152, 0xffff0000, v152
	v_lshlrev_b32_e32 v217, 16, v153
	v_and_b32_e32 v153, 0xffff0000, v153
	v_fmac_f32_e32 v62, s45, v216
	v_fmac_f32_e32 v63, s45, v152
	v_fmac_f32_e32 v64, s45, v217
	v_fmac_f32_e32 v65, s45, v153
	global_store_dwordx4 v[140:141], v[62:65], off offset:128
	v_lshlrev_b32_e32 v216, 16, v154
	v_and_b32_e32 v154, 0xffff0000, v154
	v_lshlrev_b32_e32 v217, 16, v155
	v_and_b32_e32 v155, 0xffff0000, v155
	v_fmac_f32_e32 v30, s45, v216
	v_fmac_f32_e32 v31, s45, v154
	v_fmac_f32_e32 v32, s45, v217
	v_fmac_f32_e32 v33, s45, v155
	global_store_dwordx4 v[140:141], v[30:33], off offset:192
	v_lshl_add_u64 v[140:141], v[140:141], 0, s[10:11]
	s_waitcnt vmcnt(17)
	v_permlane16_swap_b32_e32 v156, v158
	v_permlane16_swap_b32_e32 v157, v159
	v_lshlrev_b32_e32 v216, 16, v156
	v_and_b32_e32 v156, 0xffff0000, v156
	v_lshlrev_b32_e32 v217, 16, v157
	v_and_b32_e32 v157, 0xffff0000, v157
	v_fmac_f32_e32 v122, s45, v216
	v_fmac_f32_e32 v123, s45, v156
	v_fmac_f32_e32 v124, s45, v217
	v_fmac_f32_e32 v125, s45, v157
	global_store_dwordx4 v[140:141], v[122:125], off offset:0
	v_lshlrev_b32_e32 v216, 16, v158
	v_and_b32_e32 v158, 0xffff0000, v158
	v_lshlrev_b32_e32 v217, 16, v159
	v_and_b32_e32 v159, 0xffff0000, v159
	v_fmac_f32_e32 v90, s45, v216
	v_fmac_f32_e32 v91, s45, v158
	v_fmac_f32_e32 v92, s45, v217
	v_fmac_f32_e32 v93, s45, v159
	global_store_dwordx4 v[140:141], v[90:93], off offset:64
	s_waitcnt vmcnt(18)
; DEVI float blo(unsigned u) { return __uint_as_float(u << 16); }
; DEVI float bhi(unsigned u) { return __uint_as_float(u & 0xffff0000u); }
;     ...
; #pragma unroll
;       for (int nf = 0; nf < 4; nf++) {
;         const int col = n0 + wn * 64 + nf * 16 + quad * 4;
;         f32x4 a = acc[nf][mf];
;         if (EPI == EPI_RESID || EPI == EPI_RESID_ATOMIC) {
;           f32x4 x = a;
;           if (EPI == EPI_RESID || kpart == 0) {
;             const u32x2 xr = *(const u32x2*)((const u16*)(p.ws + WS_XB) + (size_t)row * 1024 + col);
;             x[0] += ALPHA * blo(xr[0]); x[1] += ALPHA * bhi(xr[0]); x[2] += ALPHA * blo(xr[1]); x[3] += ALPHA * bhi(xr[1]);
;           }
;           if (EPI == EPI_RESID) *(f32x4*)((float*)(p.ws + WS_XF) + (size_t)row * 1024 + col) = x;
;           else *(f32x4*)((float*)(p.ws + WS_SLAB) + ((size_t)kpart * 512 + (row - T_P)) * 1024 + col) = x;
	v_permlane16_swap_b32_e32 v162, v164
	v_permlane16_swap_b32_e32 v163, v165
	v_lshlrev_b32_e32 v216, 16, v162
	v_and_b32_e32 v162, 0xffff0000, v162
	v_lshlrev_b32_e32 v217, 16, v163
	v_and_b32_e32 v163, 0xffff0000, v163
	v_fmac_f32_e32 v58, s45, v216
	v_fmac_f32_e32 v59, s45, v162
	v_fmac_f32_e32 v60, s45, v217
	v_fmac_f32_e32 v61, s45, v163
	global_store_dwordx4 v[140:141], v[58:61], off offset:128
	v_lshlrev_b32_e32 v216, 16, v164
	v_and_b32_e32 v164, 0xffff0000, v164
	v_lshlrev_b32_e32 v217, 16, v165
	v_and_b32_e32 v165, 0xffff0000, v165
	v_fmac_f32_e32 v26, s45, v216
	v_fmac_f32_e32 v27, s45, v164
	v_fmac_f32_e32 v28, s45, v217
	v_fmac_f32_e32 v29, s45, v165
	global_store_dwordx4 v[140:141], v[26:29], off offset:192
	v_lshl_add_u64 v[140:141], v[140:141], 0, s[10:11]
	s_waitcnt vmcnt(19)
	v_permlane16_swap_b32_e32 v166, v168
	v_permlane16_swap_b32_e32 v167, v169
	v_lshlrev_b32_e32 v216, 16, v166
	v_and_b32_e32 v166, 0xffff0000, v166
	v_lshlrev_b32_e32 v217, 16, v167
	v_and_b32_e32 v167, 0xffff0000, v167
	v_fmac_f32_e32 v118, s45, v216
	v_fmac_f32_e32 v119, s45, v166
	v_fmac_f32_e32 v120, s45, v217
	v_fmac_f32_e32 v121, s45, v167
	global_store_dwordx4 v[140:141], v[118:121], off offset:0
	v_lshlrev_b32_e32 v216, 16, v168
	v_and_b32_e32 v168, 0xffff0000, v168
	v_lshlrev_b32_e32 v217, 16, v169
	v_and_b32_e32 v169, 0xffff0000, v169
	v_fmac_f32_e32 v86, s45, v216
	v_fmac_f32_e32 v87, s45, v168
	v_fmac_f32_e32 v88, s45, v217
	v_fmac_f32_e32 v89, s45, v169
	global_store_dwordx4 v[140:141], v[86:89], off offset:64
	s_waitcnt vmcnt(20)
	v_permlane16_swap_b32_e32 v170, v172
	v_permlane16_swap_b32_e32 v171, v173
	v_lshlrev_b32_e32 v216, 16, v170
	v_and_b32_e32 v170, 0xffff0000, v170
	v_lshlrev_b32_e32 v217, 16, v171
	v_and_b32_e32 v171, 0xffff0000, v171
	v_fmac_f32_e32 v54, s45, v216
	v_fmac_f32_e32 v55, s45, v170
	v_fmac_f32_e32 v56, s45, v217
	v_fmac_f32_e32 v57, s45, v171
	global_store_dwordx4 v[140:141], v[54:57], off offset:128
	v_lshlrev_b32_e32 v216, 16, v172
	v_and_b32_e32 v172, 0xffff0000, v172
	v_lshlrev_b32_e32 v217, 16, v173
	v_and_b32_e32 v173, 0xffff0000, v173
	v_fmac_f32_e32 v22, s45, v216
	v_fmac_f32_e32 v23, s45, v172
	v_fmac_f32_e32 v24, s45, v217
	v_fmac_f32_e32 v25, s45, v173
	global_store_dwordx4 v[140:141], v[22:25], off offset:192
	v_lshl_add_u64 v[140:141], v[140:141], 0, s[10:11]
	s_waitcnt vmcnt(21)
	v_permlane16_swap_b32_e32 v176, v178
	v_permlane16_swap_b32_e32 v177, v179
	v_lshlrev_b32_e32 v216, 16, v176
	v_and_b32_e32 v176, 0xffff0000, v176
	v_lshlrev_b32_e32 v217, 16, v177
	v_and_b32_e32 v177, 0xffff0000, v177
	v_fmac_f32_e32 v114, s45, v216
	v_fmac_f32_e32 v115, s45, v176
	v_fmac_f32_e32 v116, s45, v217
	v_fmac_f32_e32 v117, s45, v177
	global_store_dwordx4 v[140:141], v[114:117], off offset:0
	v_lshlrev_b32_e32 v216, 16, v178
	v_and_b32_e32 v178, 0xffff0000, v178
	v_lshlrev_b32_e32 v217, 16, v179
	v_and_b32_e32 v179, 0xffff0000, v179
	v_fmac_f32_e32 v82, s45, v216
	v_fmac_f32_e32 v83, s45, v178
	v_fmac_f32_e32 v84, s45, v217
	v_fmac_f32_e32 v85, s45, v179
	global_store_dwordx4 v[140:141], v[82:85], off offset:64
	s_waitcnt vmcnt(22)
	v_permlane16_swap_b32_e32 v180, v182
	v_permlane16_swap_b32_e32 v181, v183
	v_lshlrev_b32_e32 v216, 16, v180
	v_and_b32_e32 v180, 0xffff0000, v180
	v_lshlrev_b32_e32 v217, 16, v181
	v_and_b32_e32 v181, 0xffff0000, v181
	v_fmac_f32_e32 v50, s45, v216
	v_fmac_f32_e32 v51, s45, v180
	v_fmac_f32_e32 v52, s45, v217
	v_fmac_f32_e32 v53, s45, v181
	global_store_dwordx4 v[140:141], v[50:53], off offset:128
	v_lshlrev_b32_e32 v216, 16, v182
	v_and_b32_e32 v182, 0xffff0000, v182
	v_lshlrev_b32_e32 v217, 16, v183
	v_and_b32_e32 v183, 0xffff0000, v183
	v_fmac_f32_e32 v18, s45, v216
	v_fmac_f32_e32 v19, s45, v182
	v_fmac_f32_e32 v20, s45, v217
	v_fmac_f32_e32 v21, s45, v183
	global_store_dwordx4 v[140:141], v[18:21], off offset:192
	v_lshl_add_u64 v[140:141], v[140:141], 0, s[10:11]
	s_waitcnt vmcnt(23)
	v_permlane16_swap_b32_e32 v184, v186
	v_permlane16_swap_b32_e32 v185, v187
	v_lshlrev_b32_e32 v216, 16, v184
	v_and_b32_e32 v184, 0xffff0000, v184
	v_lshlrev_b32_e32 v217, 16, v185
	v_and_b32_e32 v185, 0xffff0000, v185
	v_fmac_f32_e32 v110, s45, v216
	v_fmac_f32_e32 v111, s45, v184
	v_fmac_f32_e32 v112, s45, v217
	v_fmac_f32_e32 v113, s45, v185
	global_store_dwordx4 v[140:141], v[110:113], off offset:0
	v_lshlrev_b32_e32 v216, 16, v186
	v_and_b32_e32 v186, 0xffff0000, v186
	v_lshlrev_b32_e32 v217, 16, v187
	v_and_b32_e32 v187, 0xffff0000, v187
	v_fmac_f32_e32 v78, s45, v216
	v_fmac_f32_e32 v79, s45, v186
	v_fmac_f32_e32 v80, s45, v217
	v_fmac_f32_e32 v81, s45, v187
	global_store_dwordx4 v[140:141], v[78:81], off offset:64
	s_waitcnt vmcnt(24)
	v_permlane16_swap_b32_e32 v188, v190
	v_permlane16_swap_b32_e32 v189, v191
	v_lshlrev_b32_e32 v216, 16, v188
	v_and_b32_e32 v188, 0xffff0000, v188
	v_lshlrev_b32_e32 v217, 16, v189
	v_and_b32_e32 v189, 0xffff0000, v189
	v_fmac_f32_e32 v46, s45, v216
	v_fmac_f32_e32 v47, s45, v188
	v_fmac_f32_e32 v48, s45, v217
	v_fmac_f32_e32 v49, s45, v189
	global_store_dwordx4 v[140:141], v[46:49], off offset:128
	v_lshlrev_b32_e32 v216, 16, v190
	v_and_b32_e32 v190, 0xffff0000, v190
	v_lshlrev_b32_e32 v217, 16, v191
	v_and_b32_e32 v191, 0xffff0000, v191
	v_fmac_f32_e32 v14, s45, v216
	v_fmac_f32_e32 v15, s45, v190
	v_fmac_f32_e32 v16, s45, v217
	v_fmac_f32_e32 v17, s45, v191
	global_store_dwordx4 v[140:141], v[14:17], off offset:192
	v_lshl_add_u64 v[140:141], v[140:141], 0, s[10:11]
	s_waitcnt vmcnt(25)
; DEVI float blo(unsigned u) { return __uint_as_float(u << 16); }
; DEVI float bhi(unsigned u) { return __uint_as_float(u & 0xffff0000u); }
; DEVI int xcd_first_tile() { return (blockIdx.x & 7) * (gridDim.x >> 3) + (blockIdx.x >> 3); }
;     ...
; #pragma unroll
;       for (int nf = 0; nf < 4; nf++) {
;         const int col = n0 + wn * 64 + nf * 16 + quad * 4;
;         f32x4 a = acc[nf][mf];
;         if (EPI == EPI_RESID || EPI == EPI_RESID_ATOMIC) {
;           f32x4 x = a;
;           if (EPI == EPI_RESID || kpart == 0) {
;             const u32x2 xr = *(const u32x2*)((const u16*)(p.ws + WS_XB) + (size_t)row * 1024 + col);
;             x[0] += ALPHA * blo(xr[0]); x[1] += ALPHA * bhi(xr[0]); x[2] += ALPHA * blo(xr[1]); x[3] += ALPHA * bhi(xr[1]);
;           }
;           if (EPI == EPI_RESID) *(f32x4*)((float*)(p.ws + WS_XF) + (size_t)row * 1024 + col) = x;
;           else *(f32x4*)((float*)(p.ws + WS_SLAB) + ((size_t)kpart * 512 + (row - T_P)) * 1024 + col) = x;
; DEVI void run_phase(const Params& p, int ph, char* smem) {
;     ...
;       for (int t = xcd_first_tile(); t < 512 + 16 * 8; t += xcd_tile_step()) {
;         if (t < 512) {
;           int mt_, nt_; tile_coords(t, 64, 8, mt_, nt_);
;           gemm_tile256<EPI_RESID>(p, mix, 1024, Bt, 1024, mt_ * 256, nt_ * 128, nullptr, 0, smem);
;         } else {
;           const int u_ = t - 512, tl_ = u_ / 8, q_ = u_ - tl_ * 8;
;           gemm_tile256<EPI_RESID_ATOMIC>(p, mix, 1024, Bt, 1024, (64 + (tl_ & 1)) * 256, (tl_ >> 1) * 128, nullptr, 0, smem, q_ * 128, 4, q_);
;         }
	v_permlane16_swap_b32_e32 v192, v194
	v_permlane16_swap_b32_e32 v193, v195
	v_lshlrev_b32_e32 v216, 16, v192
	v_and_b32_e32 v192, 0xffff0000, v192
	v_lshlrev_b32_e32 v217, 16, v193
	v_and_b32_e32 v193, 0xffff0000, v193
	v_fmac_f32_e32 v106, s45, v216
	v_fmac_f32_e32 v107, s45, v192
	v_fmac_f32_e32 v108, s45, v217
	v_fmac_f32_e32 v109, s45, v193
	global_store_dwordx4 v[140:141], v[106:109], off offset:0
	v_lshlrev_b32_e32 v216, 16, v194
	v_and_b32_e32 v194, 0xffff0000, v194
	v_lshlrev_b32_e32 v217, 16, v195
	v_and_b32_e32 v195, 0xffff0000, v195
	v_fmac_f32_e32 v74, s45, v216
	v_fmac_f32_e32 v75, s45, v194
	v_fmac_f32_e32 v76, s45, v217
	v_fmac_f32_e32 v77, s45, v195
	global_store_dwordx4 v[140:141], v[74:77], off offset:64
	s_waitcnt vmcnt(26)
	v_permlane16_swap_b32_e32 v196, v198
	v_permlane16_swap_b32_e32 v197, v199
	v_lshlrev_b32_e32 v216, 16, v196
	v_and_b32_e32 v196, 0xffff0000, v196
	v_lshlrev_b32_e32 v217, 16, v197
	v_and_b32_e32 v197, 0xffff0000, v197
	v_fmac_f32_e32 v42, s45, v216
	v_fmac_f32_e32 v43, s45, v196
	v_fmac_f32_e32 v44, s45, v217
	v_fmac_f32_e32 v45, s45, v197
	global_store_dwordx4 v[140:141], v[42:45], off offset:128
	v_lshlrev_b32_e32 v216, 16, v198
	v_and_b32_e32 v198, 0xffff0000, v198
	v_lshlrev_b32_e32 v217, 16, v199
	v_and_b32_e32 v199, 0xffff0000, v199
	v_fmac_f32_e32 v10, s45, v216
	v_fmac_f32_e32 v11, s45, v198
	v_fmac_f32_e32 v12, s45, v217
	v_fmac_f32_e32 v13, s45, v199
	global_store_dwordx4 v[140:141], v[10:13], off offset:192
	v_lshl_add_u64 v[140:141], v[140:141], 0, s[10:11]
	s_waitcnt vmcnt(27)
	v_permlane16_swap_b32_e32 v200, v202
	v_permlane16_swap_b32_e32 v201, v203
	v_lshlrev_b32_e32 v216, 16, v200
	v_and_b32_e32 v200, 0xffff0000, v200
	v_lshlrev_b32_e32 v217, 16, v201
	v_and_b32_e32 v201, 0xffff0000, v201
	v_fmac_f32_e32 v102, s45, v216
	v_fmac_f32_e32 v103, s45, v200
	v_fmac_f32_e32 v104, s45, v217
	v_fmac_f32_e32 v105, s45, v201
	global_store_dwordx4 v[140:141], v[102:105], off offset:0
	v_lshlrev_b32_e32 v216, 16, v202
	v_and_b32_e32 v202, 0xffff0000, v202
	v_lshlrev_b32_e32 v217, 16, v203
	v_and_b32_e32 v203, 0xffff0000, v203
	v_fmac_f32_e32 v70, s45, v216
	v_fmac_f32_e32 v71, s45, v202
	v_fmac_f32_e32 v72, s45, v217
	v_fmac_f32_e32 v73, s45, v203
	global_store_dwordx4 v[140:141], v[70:73], off offset:64
	s_waitcnt vmcnt(28)
	v_permlane16_swap_b32_e32 v204, v206
	v_permlane16_swap_b32_e32 v205, v207
	v_lshlrev_b32_e32 v216, 16, v204
	v_and_b32_e32 v204, 0xffff0000, v204
	v_lshlrev_b32_e32 v217, 16, v205
	v_and_b32_e32 v205, 0xffff0000, v205
	v_fmac_f32_e32 v38, s45, v216
	v_fmac_f32_e32 v39, s45, v204
	v_fmac_f32_e32 v40, s45, v217
	v_fmac_f32_e32 v41, s45, v205
	global_store_dwordx4 v[140:141], v[38:41], off offset:128
	v_lshlrev_b32_e32 v216, 16, v206
	v_and_b32_e32 v206, 0xffff0000, v206
	v_lshlrev_b32_e32 v217, 16, v207
	v_and_b32_e32 v207, 0xffff0000, v207
	v_fmac_f32_e32 v6, s45, v216
	v_fmac_f32_e32 v7, s45, v206
	v_fmac_f32_e32 v8, s45, v217
	v_fmac_f32_e32 v9, s45, v207
	global_store_dwordx4 v[140:141], v[6:9], off offset:192
	v_lshl_add_u64 v[140:141], v[140:141], 0, s[10:11]
	s_waitcnt vmcnt(29)
	v_permlane16_swap_b32_e32 v208, v210
	v_permlane16_swap_b32_e32 v209, v211
	v_lshlrev_b32_e32 v216, 16, v208
	v_and_b32_e32 v208, 0xffff0000, v208
	v_lshlrev_b32_e32 v217, 16, v209
	v_and_b32_e32 v209, 0xffff0000, v209
	v_fmac_f32_e32 v98, s45, v216
	v_fmac_f32_e32 v99, s45, v208
	v_fmac_f32_e32 v100, s45, v217
	v_fmac_f32_e32 v101, s45, v209
	global_store_dwordx4 v[140:141], v[98:101], off offset:0
	v_lshlrev_b32_e32 v216, 16, v210
	v_and_b32_e32 v210, 0xffff0000, v210
	v_lshlrev_b32_e32 v217, 16, v211
	v_and_b32_e32 v211, 0xffff0000, v211
	v_fmac_f32_e32 v66, s45, v216
	v_fmac_f32_e32 v67, s45, v210
	v_fmac_f32_e32 v68, s45, v217
	v_fmac_f32_e32 v69, s45, v211
	global_store_dwordx4 v[140:141], v[66:69], off offset:64
	s_waitcnt vmcnt(30)
	v_permlane16_swap_b32_e32 v212, v214
	v_permlane16_swap_b32_e32 v213, v215
	v_lshlrev_b32_e32 v216, 16, v212
	v_and_b32_e32 v212, 0xffff0000, v212
	v_lshlrev_b32_e32 v217, 16, v213
	v_and_b32_e32 v213, 0xffff0000, v213
	v_fmac_f32_e32 v34, s45, v216
	v_fmac_f32_e32 v35, s45, v212
	v_fmac_f32_e32 v36, s45, v217
	v_fmac_f32_e32 v37, s45, v213
	global_store_dwordx4 v[140:141], v[34:37], off offset:128
	v_lshlrev_b32_e32 v216, 16, v214
	v_and_b32_e32 v214, 0xffff0000, v214
	v_lshlrev_b32_e32 v217, 16, v215
	v_and_b32_e32 v215, 0xffff0000, v215
	v_fmac_f32_e32 v2, s45, v216
	v_fmac_f32_e32 v3, s45, v214
	v_fmac_f32_e32 v4, s45, v217
	v_fmac_f32_e32 v5, s45, v215
	global_store_dwordx4 v[140:141], v[2:5], off offset:192
	v_readlane_b32 s40, v250, 7
	s_cmpk_lg_u32 s40, 0x200
	s_cbranch_scc1 .LBB0_757
	v_readlane_b32 s41, v250, 0
	s_lshr_b32 s42, s41, 3
	s_and_b32 s41, s41, 7
	s_mul_i32 s41, s41, 16
	s_add_i32 s41, s41, s42
	s_cmp_lt_u32 s42, 16
	s_cselect_b32 s39, s41, 0x4000
	s_branch .LBB0_757
